# hand transposers P0/P3, W2T staging batch, counted vmcnt in P6 window/slc rings, hand-written one-hop grid barrier
# speedup vs baseline: 1.0065x; 1.0065x over previous
.LBB0_7:
	s_nop 0
	v_readlane_b32 s0, v254, 2
	v_readlane_b32 s1, v254, 3
	v_writelane_b32 v254, s48, 40
	s_cmp_lt_i32 s0, 1
	s_cselect_b64 s[4:5], -1, 0
	v_writelane_b32 v254, s49, 41
	v_writelane_b32 v254, s50, 42
	s_cmp_gt_i32 s1, 0
	v_writelane_b32 v254, s51, 43
	s_cselect_b64 s[6:7], -1, 0
	v_writelane_b32 v254, s52, 44
	s_and_b64 s[6:7], s[4:5], s[6:7]
	v_writelane_b32 v254, s53, 45
	s_andn2_b64 vcc, exec, s[6:7]
	v_and_b32_e32 v206, 63, v0
	v_writelane_b32 v254, s54, 46
	v_writelane_b32 v254, s55, 47
	s_cbranch_vccnz .LBB0_113
	v_readlane_b32 s0, v254, 0
	v_readlane_b32 s1, v254, 1
	s_load_dword s8, s[0:1], 0xe8
	v_readfirstlane_b32 s0, v0
	s_lshr_b32 s9, s0, 6
	s_lshl_b32 s0, s2, 3
	s_add_i32 s10, s9, s0
	s_waitcnt lgkmcnt(0)
	s_lshl_b32 s3, s8, 3
	s_cmpk_gt_i32 s10, 0x267f
	v_and_b32_e32 v34, 63, v0
	s_cbranch_scc1 .LBB0_78
	s_mov_b64 exec, -1
	v_readlane_b32 s0, v254, 0
	v_readlane_b32 s1, v254, 1
	s_nop 4
	s_load_dwordx2 s[56:57], s[0:1], 0x50
	s_load_dwordx2 s[58:59], s[0:1], 0x98
	s_load_dwordx2 s[60:61], s[0:1], 0x60
	s_load_dwordx2 s[62:63], s[0:1], 0xd8
	s_load_dwordx2 s[64:65], s[0:1], 0x48
	v_readfirstlane_b32 s4, v0
	v_and_b32_e32 v7, 63, v0
	s_lshr_b32 s4, s4, 6
	v_lshrrev_b32_e32 v1, 3, v7
	v_and_b32_e32 v2, 7, v7
	s_lshl_b32 s5, s4, 14
	v_lshlrev_b32_e32 v5, 5, v2
	s_movk_i32 s18, 0x420
	v_mul_u32_u24_e32 v4, s18, v2
	v_lshlrev_b32_e32 v2, 4, v2
	s_movk_i32 s18, 0x84
	v_mad_u32_u24 v3, v1, s18, v2
	v_lshl_add_u32 v4, v1, 2, v4
	v_add_u32_e32 v3, s5, v3
	v_add_u32_e32 v4, s5, v4
	v_mov_b32_e32 v148, v3
	v_add_u32_e32 v149, 1056, v3
	v_add_u32_e32 v150, 2112, v3
	v_add_u32_e32 v151, 3168, v3
	v_add_u32_e32 v152, 4224, v3
	v_add_u32_e32 v153, 5280, v3
	v_add_u32_e32 v154, 6336, v3
	v_add_u32_e32 v155, 7392, v3
	s_waitcnt lgkmcnt(0)
	s_mov_b32 s20, s10
	s_mov_b32 s21, s3
	s_cmp_ge_u32 s20, 0x2680
	s_cbranch_scc1 .LBB0_78
	s_mov_b32 s26, s20
	s_cmp_lt_u32 s26, 0x2080
	s_cbranch_scc1 .Ltrp0_i1_s0
	s_sub_u32 s26, s26, 0x2080
	s_cmp_lt_u32 s26, 0x400
	s_cbranch_scc1 .Ltrp0_i1_s1
	s_sub_u32 s26, s26, 0x400
	s_cmp_lt_u32 s26, 0x100
	s_cbranch_scc1 .Ltrp0_i1_s2
	s_sub_u32 s26, s26, 0x100
	s_branch .Ltrp0_i1_s3
.Ltrp0_i1_s0:
	s_mov_b64 s[22:23], s[56:57]
	s_mov_b32 s24, 0x8200
	s_mul_hi_u32 s25, s26, 0xfc0fc1
	s_mul_i32 s27, s25, 0x104
	s_sub_u32 s27, s26, s27
	s_mov_b32 s28, 0x100000
	s_mov_b32 s29, 0x1000
	s_mov_b32 s30, 0
	s_mov_b32 s31, 0
	s_branch .Ltrp0_i1_c
.Ltrp0_i1_s1:
	s_mov_b64 s[22:23], s[58:59]
	s_mov_b32 s24, 0x1000
	s_lshr_b32 s25, s26, 5
	s_and_b32 s27, s26, 31
	s_mov_b32 s28, 0x3400000
	s_mov_b32 s29, 0x1000
	s_mov_b32 s30, 0
	s_mov_b32 s31, 0
	s_branch .Ltrp0_i1_c
.Ltrp0_i1_s2:
	s_mov_b64 s[22:23], s[60:61]
	s_mov_b32 s24, 0x400
	s_lshr_b32 s25, s26, 3
	s_and_b32 s27, s26, 7
	s_mov_b32 s28, 0x7c00000
	s_mov_b32 s29, 0x1000
	s_mov_b32 s30, 0
	s_mov_b32 s31, 0
	s_branch .Ltrp0_i1_c
.Ltrp0_i1_s3:
	s_add_u32 s22, s60, 0x200000
	s_addc_u32 s23, s61, 0
	s_mov_b32 s24, 0x400
	s_lshr_b32 s25, s26, 3
	s_and_b32 s27, s26, 7
	s_mov_b32 s28, 0x7d00000
	s_mov_b32 s29, 0x1000
	s_mov_b32 s30, 0
	s_mov_b32 s31, 0
.Ltrp0_i1_c:
	s_lshl_b32 s4, s24, 6
	s_mul_i32 s4, s25, s4
	s_lshl_b32 s5, s27, 7
	s_add_u32 s4, s4, s5
	s_add_u32 s14, s22, s4
	s_addc_u32 s15, s23, 0
	v_mad_u32_u24 v6, v1, s24, v2
	s_lshl_b32 s4, s29, 5
	s_mul_i32 s4, s27, s4
	s_lshl_b32 s5, s25, 7
	s_add_u32 s4, s4, s5
	s_add_u32 s4, s4, s28
	s_add_u32 s34, s62, s4
	s_addc_u32 s35, s63, 0
	s_mov_b32 s36, s29
	s_mov_b32 s37, s31
	s_lshl_b32 s4, s25, 8
	s_add_u32 s4, s4, s30
	s_add_u32 s16, s64, s4
	s_addc_u32 s17, s65, 0
	s_lshl_b32 s18, s24, 3
	global_load_dwordx4 v[68:71], v6, s[14:15]
	s_add_u32 s14, s14, s18
	s_addc_u32 s15, s15, 0
	global_load_dwordx4 v[72:75], v6, s[14:15]
	s_add_u32 s14, s14, s18
	s_addc_u32 s15, s15, 0
	global_load_dwordx4 v[76:79], v6, s[14:15]
	s_add_u32 s14, s14, s18
	s_addc_u32 s15, s15, 0
	global_load_dwordx4 v[80:83], v6, s[14:15]
	s_add_u32 s14, s14, s18
	s_addc_u32 s15, s15, 0
	global_load_dwordx4 v[84:87], v6, s[14:15]
	s_add_u32 s14, s14, s18
	s_addc_u32 s15, s15, 0
	global_load_dwordx4 v[88:91], v6, s[14:15]
	s_add_u32 s14, s14, s18
	s_addc_u32 s15, s15, 0
	global_load_dwordx4 v[92:95], v6, s[14:15]
	s_add_u32 s14, s14, s18
	s_addc_u32 s15, s15, 0
	global_load_dwordx4 v[96:99], v6, s[14:15]
	global_load_dwordx4 v[100:103], v5, s[16:17]
	global_load_dwordx4 v[104:107], v5, s[16:17] offset:16
	s_add_u32 s20, s20, s21
	s_cmp_ge_u32 s20, 0x2680
	s_mov_b32 s43, 0
	s_cbranch_scc1 .Ltrp0_pro_nob
	s_mov_b32 s26, s20
	s_cmp_lt_u32 s26, 0x2080
	s_cbranch_scc1 .Ltrp0_i2_s0
	s_sub_u32 s26, s26, 0x2080
	s_cmp_lt_u32 s26, 0x400
	s_cbranch_scc1 .Ltrp0_i2_s1
	s_sub_u32 s26, s26, 0x400
	s_cmp_lt_u32 s26, 0x100
	s_cbranch_scc1 .Ltrp0_i2_s2
	s_sub_u32 s26, s26, 0x100
	s_branch .Ltrp0_i2_s3

.Ltrp0_i2_c:
	s_lshl_b32 s4, s24, 6
	s_mul_i32 s4, s25, s4
	s_lshl_b32 s5, s27, 7
	s_add_u32 s4, s4, s5
	s_add_u32 s14, s22, s4
	s_addc_u32 s15, s23, 0
	v_mad_u32_u24 v6, v1, s24, v2
	s_lshl_b32 s4, s29, 5
	s_mul_i32 s4, s27, s4
	s_lshl_b32 s5, s25, 7
	s_add_u32 s4, s4, s5
	s_add_u32 s4, s4, s28
	s_add_u32 s38, s62, s4
	s_addc_u32 s39, s63, 0
	s_mov_b32 s40, s29
	s_mov_b32 s41, s31
	s_lshl_b32 s4, s25, 8
	s_add_u32 s4, s4, s30
	s_add_u32 s16, s64, s4
	s_addc_u32 s17, s65, 0
	s_lshl_b32 s18, s24, 3
	global_load_dwordx4 v[108:111], v6, s[14:15]
	s_add_u32 s14, s14, s18
	s_addc_u32 s15, s15, 0
	global_load_dwordx4 v[112:115], v6, s[14:15]
	s_add_u32 s14, s14, s18
	s_addc_u32 s15, s15, 0
	global_load_dwordx4 v[116:119], v6, s[14:15]
	s_add_u32 s14, s14, s18
	s_addc_u32 s15, s15, 0
	global_load_dwordx4 v[120:123], v6, s[14:15]
	s_add_u32 s14, s14, s18
	s_addc_u32 s15, s15, 0
	global_load_dwordx4 v[124:127], v6, s[14:15]
	s_add_u32 s14, s14, s18
	s_addc_u32 s15, s15, 0
	global_load_dwordx4 v[128:131], v6, s[14:15]
	s_add_u32 s14, s14, s18
	s_addc_u32 s15, s15, 0
	global_load_dwordx4 v[132:135], v6, s[14:15]
	s_add_u32 s14, s14, s18
	s_addc_u32 s15, s15, 0
	global_load_dwordx4 v[136:139], v6, s[14:15]
	global_load_dwordx4 v[140:143], v5, s[16:17]
	global_load_dwordx4 v[144:147], v5, s[16:17] offset:16
	s_add_u32 s20, s20, s21
	s_mov_b32 s43, 1
	s_waitcnt vmcnt(10)
	s_branch .Ltrp0_loopA

.Ltrp0_loopA:
	ds_write2_b32 v148, v68, v69 offset1:1
	ds_write2_b32 v148, v70, v71 offset0:2 offset1:3
	ds_write2_b32 v149, v72, v73 offset1:1
	ds_write2_b32 v149, v74, v75 offset0:2 offset1:3
	ds_write2_b32 v150, v76, v77 offset1:1
	ds_write2_b32 v150, v78, v79 offset0:2 offset1:3
	ds_write2_b32 v151, v80, v81 offset1:1
	ds_write2_b32 v151, v82, v83 offset0:2 offset1:3
	ds_write2_b32 v152, v84, v85 offset1:1
	ds_write2_b32 v152, v86, v87 offset0:2 offset1:3
	ds_write2_b32 v153, v88, v89 offset1:1
	ds_write2_b32 v153, v90, v91 offset0:2 offset1:3
	ds_write2_b32 v154, v92, v93 offset1:1
	ds_write2_b32 v154, v94, v95 offset0:2 offset1:3
	ds_write2_b32 v155, v96, v97 offset1:1
	ds_write2_b32 v155, v98, v99 offset0:2 offset1:3
	v_mad_u32_u24 v8, v1, s36, v2
	s_lshl_b32 s4, s36, 3
	s_nop 0
	v_add_u32_e32 v9, s4, v8
	v_add_u32_e32 v10, s4, v9
	v_add_u32_e32 v11, s4, v10
	s_waitcnt lgkmcnt(0)
	ds_read2_b32 v[36:37], v4 offset1:33
	ds_read2_b32 v[38:39], v4 offset0:66 offset1:99
	ds_read2_b32 v[40:41], v4 offset0:132 offset1:165
	ds_read2_b32 v[42:43], v4 offset0:198 offset1:231
	ds_read2_b32 v[44:45], v4 offset0:8 offset1:41
	ds_read2_b32 v[46:47], v4 offset0:74 offset1:107
	ds_read2_b32 v[48:49], v4 offset0:140 offset1:173
	ds_read2_b32 v[50:51], v4 offset0:206 offset1:239
	ds_read2_b32 v[52:53], v4 offset0:16 offset1:49
	ds_read2_b32 v[54:55], v4 offset0:82 offset1:115
	ds_read2_b32 v[56:57], v4 offset0:148 offset1:181
	ds_read2_b32 v[58:59], v4 offset0:214 offset1:247
	ds_read2_b32 v[60:61], v4 offset0:24 offset1:57
	ds_read2_b32 v[62:63], v4 offset0:90 offset1:123
	ds_read2_b32 v[64:65], v4 offset0:156 offset1:189
	ds_read2_b32 v[66:67], v4 offset0:222 offset1:255
	s_cmp_eq_u32 s37, 0
	s_waitcnt lgkmcnt(0)
	s_cbranch_scc1 .Ltrp0_p3_ng
	v_mul_f32_e32 v36, v100, v36
	v_mul_f32_e32 v37, v101, v37
	v_mul_f32_e32 v38, v102, v38
	v_mul_f32_e32 v39, v103, v39
	v_mul_f32_e32 v40, v104, v40
	v_mul_f32_e32 v41, v105, v41
	v_mul_f32_e32 v42, v106, v42
	v_mul_f32_e32 v43, v107, v43
	v_mul_f32_e32 v44, v100, v44
	v_mul_f32_e32 v45, v101, v45
	v_mul_f32_e32 v46, v102, v46
	v_mul_f32_e32 v47, v103, v47
	v_mul_f32_e32 v48, v104, v48
	v_mul_f32_e32 v49, v105, v49
	v_mul_f32_e32 v50, v106, v50
	v_mul_f32_e32 v51, v107, v51
	v_mul_f32_e32 v52, v100, v52
	v_mul_f32_e32 v53, v101, v53
	v_mul_f32_e32 v54, v102, v54
	v_mul_f32_e32 v55, v103, v55
	v_mul_f32_e32 v56, v104, v56
	v_mul_f32_e32 v57, v105, v57
	v_mul_f32_e32 v58, v106, v58
	v_mul_f32_e32 v59, v107, v59
	v_mul_f32_e32 v60, v100, v60
	v_mul_f32_e32 v61, v101, v61
	v_mul_f32_e32 v62, v102, v62
	v_mul_f32_e32 v63, v103, v63
	v_mul_f32_e32 v64, v104, v64
	v_mul_f32_e32 v65, v105, v65
	v_mul_f32_e32 v66, v106, v66
	v_mul_f32_e32 v67, v107, v67
.Ltrp0_p3_ng:
	v_cvt_pk_bf16_f32 v36, v36, v37
	v_cvt_pk_bf16_f32 v37, v38, v39
	v_cvt_pk_bf16_f32 v38, v40, v41
	v_cvt_pk_bf16_f32 v39, v42, v43
	v_cvt_pk_bf16_f32 v44, v44, v45
	v_cvt_pk_bf16_f32 v45, v46, v47
	v_cvt_pk_bf16_f32 v46, v48, v49
	v_cvt_pk_bf16_f32 v47, v50, v51
	v_cvt_pk_bf16_f32 v52, v52, v53
	v_cvt_pk_bf16_f32 v53, v54, v55
	v_cvt_pk_bf16_f32 v54, v56, v57
	v_cvt_pk_bf16_f32 v55, v58, v59
	v_cvt_pk_bf16_f32 v60, v60, v61
	v_cvt_pk_bf16_f32 v61, v62, v63
	v_cvt_pk_bf16_f32 v62, v64, v65
	v_cvt_pk_bf16_f32 v63, v66, v67
	global_store_dwordx4 v8, v[36:39], s[34:35]
	global_store_dwordx4 v9, v[44:47], s[34:35]
	global_store_dwordx4 v10, v[52:55], s[34:35]
	global_store_dwordx4 v11, v[60:63], s[34:35]
	s_cmp_ge_u32 s20, 0x2680
	s_mov_b32 s42, 0
	s_cbranch_scc1 .Ltrp0_skipA
	s_mov_b32 s26, s20
	s_cmp_lt_u32 s26, 0x2080
	s_cbranch_scc1 .Ltrp0_i4_s0
	s_sub_u32 s26, s26, 0x2080
	s_cmp_lt_u32 s26, 0x400
	s_cbranch_scc1 .Ltrp0_i4_s1
	s_sub_u32 s26, s26, 0x400
	s_cmp_lt_u32 s26, 0x100
	s_cbranch_scc1 .Ltrp0_i4_s2
	s_sub_u32 s26, s26, 0x100
	s_branch .Ltrp0_i4_s3

.Ltrp0_i4_c:
	s_lshl_b32 s4, s24, 6
	s_mul_i32 s4, s25, s4
	s_lshl_b32 s5, s27, 7
	s_add_u32 s4, s4, s5
	s_add_u32 s14, s22, s4
	s_addc_u32 s15, s23, 0
	v_mad_u32_u24 v6, v1, s24, v2
	s_lshl_b32 s4, s29, 5
	s_mul_i32 s4, s27, s4
	s_lshl_b32 s5, s25, 7
	s_add_u32 s4, s4, s5
	s_add_u32 s4, s4, s28
	s_add_u32 s34, s62, s4
	s_addc_u32 s35, s63, 0
	s_mov_b32 s36, s29
	s_mov_b32 s37, s31
	s_lshl_b32 s4, s25, 8
	s_add_u32 s4, s4, s30
	s_add_u32 s16, s64, s4
	s_addc_u32 s17, s65, 0
	s_lshl_b32 s18, s24, 3
	global_load_dwordx4 v[68:71], v6, s[14:15]
	s_add_u32 s14, s14, s18
	s_addc_u32 s15, s15, 0
	global_load_dwordx4 v[72:75], v6, s[14:15]
	s_add_u32 s14, s14, s18
	s_addc_u32 s15, s15, 0
	global_load_dwordx4 v[76:79], v6, s[14:15]
	s_add_u32 s14, s14, s18
	s_addc_u32 s15, s15, 0
	global_load_dwordx4 v[80:83], v6, s[14:15]
	s_add_u32 s14, s14, s18
	s_addc_u32 s15, s15, 0
	global_load_dwordx4 v[84:87], v6, s[14:15]
	s_add_u32 s14, s14, s18
	s_addc_u32 s15, s15, 0
	global_load_dwordx4 v[88:91], v6, s[14:15]
	s_add_u32 s14, s14, s18
	s_addc_u32 s15, s15, 0
	global_load_dwordx4 v[92:95], v6, s[14:15]
	s_add_u32 s14, s14, s18
	s_addc_u32 s15, s15, 0
	global_load_dwordx4 v[96:99], v6, s[14:15]
	global_load_dwordx4 v[100:103], v5, s[16:17]
	global_load_dwordx4 v[104:107], v5, s[16:17] offset:16
	s_add_u32 s20, s20, s21
	s_mov_b32 s42, 1

.Ltrp0_doB:
	ds_write2_b32 v148, v108, v109 offset1:1
	ds_write2_b32 v148, v110, v111 offset0:2 offset1:3
	ds_write2_b32 v149, v112, v113 offset1:1
	ds_write2_b32 v149, v114, v115 offset0:2 offset1:3
	ds_write2_b32 v150, v116, v117 offset1:1
	ds_write2_b32 v150, v118, v119 offset0:2 offset1:3
	ds_write2_b32 v151, v120, v121 offset1:1
	ds_write2_b32 v151, v122, v123 offset0:2 offset1:3
	ds_write2_b32 v152, v124, v125 offset1:1
	ds_write2_b32 v152, v126, v127 offset0:2 offset1:3
	ds_write2_b32 v153, v128, v129 offset1:1
	ds_write2_b32 v153, v130, v131 offset0:2 offset1:3
	ds_write2_b32 v154, v132, v133 offset1:1
	ds_write2_b32 v154, v134, v135 offset0:2 offset1:3
	ds_write2_b32 v155, v136, v137 offset1:1
	ds_write2_b32 v155, v138, v139 offset0:2 offset1:3
	v_mad_u32_u24 v8, v1, s40, v2
	s_lshl_b32 s4, s40, 3
	s_nop 0
	v_add_u32_e32 v9, s4, v8
	v_add_u32_e32 v10, s4, v9
	v_add_u32_e32 v11, s4, v10
	s_waitcnt lgkmcnt(0)
	ds_read2_b32 v[36:37], v4 offset1:33
	ds_read2_b32 v[38:39], v4 offset0:66 offset1:99
	ds_read2_b32 v[40:41], v4 offset0:132 offset1:165
	ds_read2_b32 v[42:43], v4 offset0:198 offset1:231
	ds_read2_b32 v[44:45], v4 offset0:8 offset1:41
	ds_read2_b32 v[46:47], v4 offset0:74 offset1:107
	ds_read2_b32 v[48:49], v4 offset0:140 offset1:173
	ds_read2_b32 v[50:51], v4 offset0:206 offset1:239
	ds_read2_b32 v[52:53], v4 offset0:16 offset1:49
	ds_read2_b32 v[54:55], v4 offset0:82 offset1:115
	ds_read2_b32 v[56:57], v4 offset0:148 offset1:181
	ds_read2_b32 v[58:59], v4 offset0:214 offset1:247
	ds_read2_b32 v[60:61], v4 offset0:24 offset1:57
	ds_read2_b32 v[62:63], v4 offset0:90 offset1:123
	ds_read2_b32 v[64:65], v4 offset0:156 offset1:189
	ds_read2_b32 v[66:67], v4 offset0:222 offset1:255
	s_cmp_eq_u32 s41, 0
	s_waitcnt lgkmcnt(0)
	s_cbranch_scc1 .Ltrp0_p5_ng
	v_mul_f32_e32 v36, v140, v36
	v_mul_f32_e32 v37, v141, v37
	v_mul_f32_e32 v38, v142, v38
	v_mul_f32_e32 v39, v143, v39
	v_mul_f32_e32 v40, v144, v40
	v_mul_f32_e32 v41, v145, v41
	v_mul_f32_e32 v42, v146, v42
	v_mul_f32_e32 v43, v147, v43
	v_mul_f32_e32 v44, v140, v44
	v_mul_f32_e32 v45, v141, v45
	v_mul_f32_e32 v46, v142, v46
	v_mul_f32_e32 v47, v143, v47
	v_mul_f32_e32 v48, v144, v48
	v_mul_f32_e32 v49, v145, v49
	v_mul_f32_e32 v50, v146, v50
	v_mul_f32_e32 v51, v147, v51
	v_mul_f32_e32 v52, v140, v52
	v_mul_f32_e32 v53, v141, v53
	v_mul_f32_e32 v54, v142, v54
	v_mul_f32_e32 v55, v143, v55
	v_mul_f32_e32 v56, v144, v56
	v_mul_f32_e32 v57, v145, v57
	v_mul_f32_e32 v58, v146, v58
	v_mul_f32_e32 v59, v147, v59
	v_mul_f32_e32 v60, v140, v60
	v_mul_f32_e32 v61, v141, v61
	v_mul_f32_e32 v62, v142, v62
	v_mul_f32_e32 v63, v143, v63
	v_mul_f32_e32 v64, v144, v64
	v_mul_f32_e32 v65, v145, v65
	v_mul_f32_e32 v66, v146, v66
	v_mul_f32_e32 v67, v147, v67
.Ltrp0_p5_ng:
	v_cvt_pk_bf16_f32 v36, v36, v37
	v_cvt_pk_bf16_f32 v37, v38, v39
	v_cvt_pk_bf16_f32 v38, v40, v41
	v_cvt_pk_bf16_f32 v39, v42, v43
	v_cvt_pk_bf16_f32 v44, v44, v45
	v_cvt_pk_bf16_f32 v45, v46, v47
	v_cvt_pk_bf16_f32 v46, v48, v49
	v_cvt_pk_bf16_f32 v47, v50, v51
	v_cvt_pk_bf16_f32 v52, v52, v53
	v_cvt_pk_bf16_f32 v53, v54, v55
	v_cvt_pk_bf16_f32 v54, v56, v57
	v_cvt_pk_bf16_f32 v55, v58, v59
	v_cvt_pk_bf16_f32 v60, v60, v61
	v_cvt_pk_bf16_f32 v61, v62, v63
	v_cvt_pk_bf16_f32 v62, v64, v65
	v_cvt_pk_bf16_f32 v63, v66, v67
	global_store_dwordx4 v8, v[36:39], s[38:39]
	global_store_dwordx4 v9, v[44:47], s[38:39]
	global_store_dwordx4 v10, v[52:55], s[38:39]
	global_store_dwordx4 v11, v[60:63], s[38:39]
	s_cmp_ge_u32 s20, 0x2680
	s_mov_b32 s43, 0
	s_cbranch_scc1 .Ltrp0_skipB
	s_mov_b32 s26, s20
	s_cmp_lt_u32 s26, 0x2080
	s_cbranch_scc1 .Ltrp0_i6_s0
	s_sub_u32 s26, s26, 0x2080
	s_cmp_lt_u32 s26, 0x400
	s_cbranch_scc1 .Ltrp0_i6_s1
	s_sub_u32 s26, s26, 0x400
	s_cmp_lt_u32 s26, 0x100
	s_cbranch_scc1 .Ltrp0_i6_s2
	s_sub_u32 s26, s26, 0x100
	s_branch .Ltrp0_i6_s3

.Ltrp0_i6_c:
	s_lshl_b32 s4, s24, 6
	s_mul_i32 s4, s25, s4
	s_lshl_b32 s5, s27, 7
	s_add_u32 s4, s4, s5
	s_add_u32 s14, s22, s4
	s_addc_u32 s15, s23, 0
	v_mad_u32_u24 v6, v1, s24, v2
	s_lshl_b32 s4, s29, 5
	s_mul_i32 s4, s27, s4
	s_lshl_b32 s5, s25, 7
	s_add_u32 s4, s4, s5
	s_add_u32 s4, s4, s28
	s_add_u32 s38, s62, s4
	s_addc_u32 s39, s63, 0
	s_mov_b32 s40, s29
	s_mov_b32 s41, s31
	s_lshl_b32 s4, s25, 8
	s_add_u32 s4, s4, s30
	s_add_u32 s16, s64, s4
	s_addc_u32 s17, s65, 0
	s_lshl_b32 s18, s24, 3
	global_load_dwordx4 v[108:111], v6, s[14:15]
	s_add_u32 s14, s14, s18
	s_addc_u32 s15, s15, 0
	global_load_dwordx4 v[112:115], v6, s[14:15]
	s_add_u32 s14, s14, s18
	s_addc_u32 s15, s15, 0
	global_load_dwordx4 v[116:119], v6, s[14:15]
	s_add_u32 s14, s14, s18
	s_addc_u32 s15, s15, 0
	global_load_dwordx4 v[120:123], v6, s[14:15]
	s_add_u32 s14, s14, s18
	s_addc_u32 s15, s15, 0
	global_load_dwordx4 v[124:127], v6, s[14:15]
	s_add_u32 s14, s14, s18
	s_addc_u32 s15, s15, 0
	global_load_dwordx4 v[128:131], v6, s[14:15]
	s_add_u32 s14, s14, s18
	s_addc_u32 s15, s15, 0
	global_load_dwordx4 v[132:135], v6, s[14:15]
	s_add_u32 s14, s14, s18
	s_addc_u32 s15, s15, 0
	global_load_dwordx4 v[136:139], v6, s[14:15]
	global_load_dwordx4 v[140:143], v5, s[16:17]
	global_load_dwordx4 v[144:147], v5, s[16:17] offset:16
	s_add_u32 s20, s20, s21
	s_mov_b32 s43, 1

.Ltrp0_wA0:
	s_waitcnt vmcnt(0)
	s_branch .Ltrp0_loopA
.LBB0_78:
	s_cmpk_gt_i32 s10, 0x727f
	s_cbranch_scc1 .LBB0_109
	s_waitcnt vmcnt(8)
	v_mov_b32_e32 v27, 0
	v_lshlrev_b32_e32 v26, 4, v34
	v_readlane_b32 s16, v254, 4
	v_lshl_add_u64 v[2:3], s[52:53], 0, v[26:27]
	s_mov_b64 s[4:5], 0x5240000
	v_readlane_b32 s18, v254, 6
	v_readlane_b32 s19, v254, 7
	s_waitcnt vmcnt(6)
	v_lshl_add_u64 v[28:29], s[82:83], 0, v[26:27]
	s_waitcnt vmcnt(4)
	v_lshl_add_u64 v[30:31], s[80:81], 0, v[26:27]
	v_lshl_add_u64 v[32:33], v[2:3], 0, s[4:5]
	v_lshl_add_u64 v[36:37], s[18:19], 0, v[26:27]
	s_mov_b64 s[4:5], 0x4000
	v_lshlrev_b32_e32 v26, 3, v34
	v_lshl_add_u64 v[38:39], v[36:37], 0, s[4:5]
	v_lshl_add_u64 v[2:3], s[54:55], 0, v[26:27]
	s_mov_b64 s[4:5], 0x9f00000
	v_lshl_add_u64 v[40:41], v[2:3], 0, s[4:5]
	s_mov_b64 s[4:5], 0x5000
	v_lshl_add_u64 v[42:43], v[36:37], 0, s[4:5]
	s_mov_b64 s[4:5], 0x5400
	v_lshl_add_u64 v[44:45], v[36:37], 0, s[4:5]
	s_mov_b64 s[4:5], 0x5800
	v_lshl_add_u64 v[46:47], v[36:37], 0, s[4:5]
	s_mov_b64 s[4:5], 0x5c00
	v_lshl_add_u64 v[48:49], v[36:37], 0, s[4:5]
	s_mov_b64 s[4:5], 0x7e00000
	s_add_u32 s12, s54, 0x2c39a000
	v_lshl_add_u64 v[50:51], v[2:3], 0, s[4:5]
	v_bfe_u32 v2, v0, 4, 2
	s_addc_u32 s13, s55, 0
	v_readlane_b32 s20, v254, 8
	v_readlane_b32 s24, v254, 12
	v_mul_hi_u32_u24_e32 v3, 0x500, v2
	v_mul_u32_u24_e32 v2, 0x500, v2
	v_and_b32_e32 v6, 15, v0
	v_lshrrev_b32_e32 v4, 4, v34
	v_lshlrev_b32_e32 v5, 3, v0
	v_readlane_b32 s21, v254, 9
	v_readlane_b32 s25, v254, 13
	s_add_u32 s20, s24, 0x7c00
	v_lshl_or_b32 v2, v6, 4, v2
	v_readlane_b32 s23, v254, 11
	s_mov_b64 s[4:5], 0x1000
	s_addc_u32 s21, s25, 0
	s_lshl_b32 s0, s2, 5
	s_lshl_b32 s1, s9, 2
	v_lshl_add_u64 v[60:61], s[86:87], 0, v[2:3]
	v_and_or_b32 v2, v5, 48, v4
	v_and_b32_e32 v4, 1, v0
	v_lshl_add_u64 v[52:53], v[36:37], 0, s[4:5]
	s_mov_b64 s[4:5], 0x1400
	s_add_i32 s23, s0, s1
	v_lshlrev_b32_e32 v3, 7, v34
	v_lshlrev_b32_e32 v4, 3, v4
	s_movk_i32 s0, 0x400
	v_readlane_b32 s26, v254, 14
	v_lshl_add_u64 v[54:55], v[36:37], 0, s[4:5]
	s_mov_b64 s[4:5], 0x1800
	v_lshlrev_b32_e32 v2, 4, v2
	v_and_or_b32 v26, v3, s0, v4
	s_lshl_b32 s0, s2, 6
	s_lshl_b32 s1, s9, 3
	v_lshl_add_u64 v[56:57], v[36:37], 0, s[4:5]
	s_mov_b64 s[4:5], 0x1c00
	v_or_b32_e32 v62, 0xc0, v2
	v_lshl_add_u64 v[64:65], s[54:55], 0, v[26:27]
	s_add_i32 s26, s0, s1
	v_or_b32_e32 v66, 0x80, v2
	v_or_b32_e32 v68, 64, v2
	v_lshlrev_b32_e32 v2, 7, v0
	s_movk_i32 s0, 0x330
	v_lshlrev_b32_e32 v26, 3, v6
	v_readlane_b32 s22, v254, 10
	v_readlane_b32 s27, v254, 15
	v_readlane_b32 s28, v254, 16
	v_readlane_b32 s29, v254, 17
	v_readlane_b32 s30, v254, 18
	v_readlane_b32 s31, v254, 19
	v_lshl_add_u64 v[58:59], v[36:37], 0, s[4:5]
	v_bitop3_b32 v70, v2, s0, v34 bitop3:0xc8
	v_lshl_add_u64 v[2:3], s[54:55], 0, v[26:27]
	s_mov_b64 s[4:5], 0x24398400
	s_lshl_b32 s0, s2, 16
	s_lshl_b32 s1, s9, 13
	v_bfe_u32 v1, v0, 4, 1
	s_add_i32 s22, s10, 0xffffcd80
	s_lshl_b32 s24, s8, 5
	v_mov_b32_e32 v63, v27
	s_add_i32 s25, s10, 0xffffd580
	s_lshl_b32 s27, s8, 6
	v_mov_b32_e32 v67, v27
	v_mov_b32_e32 v69, v27
	v_mov_b32_e32 v71, v27
	v_lshl_add_u64 v[72:73], v[2:3], 0, s[4:5]
	s_add_i32 s28, s10, 0xffffdd80
	s_add_i32 s9, s0, s1
	s_lshl_b32 s29, s8, 16
	s_mov_b32 s15, 0
	s_movk_i32 s30, 0x1000
	s_mov_b32 s31, 0x5122a000
	s_movk_i32 s34, 0x2000
	s_movk_i32 s35, 0x4000
	s_movk_i32 s36, 0x5000
	s_mov_b32 s37, 0x5122b000
	s_movk_i32 s38, 0x6000
	s_movk_i32 s39, 0x7000
	s_mov_b32 s44, 0x5122c000
	v_mov_b32_e32 v35, 0x358637bd
	s_mov_b32 s45, 0x800000
	v_lshlrev_b32_e32 v26, 4, v34
	s_mov_b32 s56, s10
	v_readlane_b32 s17, v254, 5
	s_branch .LBB0_82

.LBB0_113:
	v_readlane_b32 s0, v254, 2
	v_readlane_b32 s1, v254, 3
	s_cmp_gt_i32 s1, 1
	s_cselect_b64 s[4:5], -1, 0
	s_and_b64 s[6:7], s[6:7], s[4:5]
	s_andn2_b64 vcc, exec, s[6:7]
	s_cbranch_vccnz .LBB0_163
	s_waitcnt vmcnt(0) lgkmcnt(0)
	s_barrier
	v_readfirstlane_b32 s0, v0
	s_lshr_b32 s0, s0, 6
	s_cmp_lg_u32 s0, 0
	s_cbranch_scc1 .Lgb0_close
	s_mov_b64 s[10:11], exec
	s_mov_b64 exec, 1
	v_readlane_b32 s12, v254, 36
	v_readlane_b32 s13, v254, 37
	v_readlane_b32 s14, v254, 38
	v_readlane_b32 s15, v254, 39
	s_nop 1
	v_mov_b32_e32 v1, s14
	ds_read_b32 v2, v1
	ds_read_b32 v3, v1 offset:4
	ds_read_b32 v4, v1 offset:8
	s_waitcnt lgkmcnt(0)
	v_readfirstlane_b32 s16, v2
	v_readfirstlane_b32 s17, v3
	v_readfirstlane_b32 s18, v4
	s_cmp_lg_u32 s16, 0
	s_cbranch_scc1 .Lgb0_have
	v_readlane_b32 s0, v254, 0
	v_readlane_b32 s1, v254, 1
	s_nop 4
	s_load_dwordx2 s[20:21], s[0:1], 0xe8
	s_load_dword s22, s[0:1], 0xf0
	v_mov_b32_e32 v5, 0
	v_mov_b32_e32 v6, 0x1000
	s_mov_b32 s19, 0
	s_waitcnt lgkmcnt(0)
	s_mul_i32 s20, s20, s21
	s_mul_i32 s20, s20, s22
.Lgb0_cen:
	global_load_dword v7, v5, s[12:13] offset:1024 sc1
	global_load_dword v8, v5, s[12:13] offset:1280 sc1
	global_load_dword v9, v5, s[12:13] offset:1536 sc1
	global_load_dword v10, v5, s[12:13] offset:1792 sc1
	global_load_dword v11, v5, s[12:13] offset:2048 sc1
	global_load_dword v12, v5, s[12:13] offset:2304 sc1
	global_load_dword v13, v5, s[12:13] offset:2560 sc1
	global_load_dword v14, v5, s[12:13] offset:2816 sc1
	global_load_dword v15, v5, s[12:13] offset:3072 sc1
	global_load_dword v16, v5, s[12:13] offset:3328 sc1
	global_load_dword v17, v5, s[12:13] offset:3584 sc1
	global_load_dword v18, v5, s[12:13] offset:3840 sc1
	global_load_dword v19, v6, s[12:13] sc1
	global_load_dword v20, v6, s[12:13] offset:256 sc1
	global_load_dword v21, v6, s[12:13] offset:512 sc1
	global_load_dword v22, v6, s[12:13] offset:768 sc1
	s_waitcnt vmcnt(0)
	s_mov_b32 s21, 0
	s_mov_b32 s23, 0
	s_mov_b32 s24, 0
	v_readfirstlane_b32 s22, v7
	s_add_u32 s21, s21, s22
	s_cmp_lg_u32 s22, 0
	s_addc_u32 s23, s23, 0
	s_cmp_eq_u32 s15, 0
	s_cselect_b32 s24, s22, s24
	v_readfirstlane_b32 s22, v8
	s_add_u32 s21, s21, s22
	s_cmp_lg_u32 s22, 0
	s_addc_u32 s23, s23, 0
	s_cmp_eq_u32 s15, 1
	s_cselect_b32 s24, s22, s24
	v_readfirstlane_b32 s22, v9
	s_add_u32 s21, s21, s22
	s_cmp_lg_u32 s22, 0
	s_addc_u32 s23, s23, 0
	s_cmp_eq_u32 s15, 2
	s_cselect_b32 s24, s22, s24
	v_readfirstlane_b32 s22, v10
	s_add_u32 s21, s21, s22
	s_cmp_lg_u32 s22, 0
	s_addc_u32 s23, s23, 0
	s_cmp_eq_u32 s15, 3
	s_cselect_b32 s24, s22, s24
	v_readfirstlane_b32 s22, v11
	s_add_u32 s21, s21, s22
	s_cmp_lg_u32 s22, 0
	s_addc_u32 s23, s23, 0
	s_cmp_eq_u32 s15, 4
	s_cselect_b32 s24, s22, s24
	v_readfirstlane_b32 s22, v12
	s_add_u32 s21, s21, s22
	s_cmp_lg_u32 s22, 0
	s_addc_u32 s23, s23, 0
	s_cmp_eq_u32 s15, 5
	s_cselect_b32 s24, s22, s24
	v_readfirstlane_b32 s22, v13
	s_add_u32 s21, s21, s22
	s_cmp_lg_u32 s22, 0
	s_addc_u32 s23, s23, 0
	s_cmp_eq_u32 s15, 6
	s_cselect_b32 s24, s22, s24
	v_readfirstlane_b32 s22, v14
	s_add_u32 s21, s21, s22
	s_cmp_lg_u32 s22, 0
	s_addc_u32 s23, s23, 0
	s_cmp_eq_u32 s15, 7
	s_cselect_b32 s24, s22, s24
	v_readfirstlane_b32 s22, v15
	s_add_u32 s21, s21, s22
	s_cmp_lg_u32 s22, 0
	s_addc_u32 s23, s23, 0
	s_cmp_eq_u32 s15, 8
	s_cselect_b32 s24, s22, s24
	v_readfirstlane_b32 s22, v16
	s_add_u32 s21, s21, s22
	s_cmp_lg_u32 s22, 0
	s_addc_u32 s23, s23, 0
	s_cmp_eq_u32 s15, 9
	s_cselect_b32 s24, s22, s24
	v_readfirstlane_b32 s22, v17
	s_add_u32 s21, s21, s22
	s_cmp_lg_u32 s22, 0
	s_addc_u32 s23, s23, 0
	s_cmp_eq_u32 s15, 10
	s_cselect_b32 s24, s22, s24
	v_readfirstlane_b32 s22, v18
	s_add_u32 s21, s21, s22
	s_cmp_lg_u32 s22, 0
	s_addc_u32 s23, s23, 0
	s_cmp_eq_u32 s15, 11
	s_cselect_b32 s24, s22, s24
	v_readfirstlane_b32 s22, v19
	s_add_u32 s21, s21, s22
	s_cmp_lg_u32 s22, 0
	s_addc_u32 s23, s23, 0
	s_cmp_eq_u32 s15, 12
	s_cselect_b32 s24, s22, s24
	v_readfirstlane_b32 s22, v20
	s_add_u32 s21, s21, s22
	s_cmp_lg_u32 s22, 0
	s_addc_u32 s23, s23, 0
	s_cmp_eq_u32 s15, 13
	s_cselect_b32 s24, s22, s24
	v_readfirstlane_b32 s22, v21
	s_add_u32 s21, s21, s22
	s_cmp_lg_u32 s22, 0
	s_addc_u32 s23, s23, 0
	s_cmp_eq_u32 s15, 14
	s_cselect_b32 s24, s22, s24
	v_readfirstlane_b32 s22, v22
	s_add_u32 s21, s21, s22
	s_cmp_lg_u32 s22, 0
	s_addc_u32 s23, s23, 0
	s_cmp_eq_u32 s15, 15
	s_cselect_b32 s24, s22, s24
	s_cmp_eq_u32 s21, s20
	s_cbranch_scc1 .Lgb0_cend
	s_sleep 1
	s_add_u32 s19, s19, 1
	s_cmp_lt_u32 s19, 0x40000
	s_cbranch_scc1 .Lgb0_cen
.Lgb0_cend:
	s_max_u32 s16, s24, 1
	s_max_u32 s17, s23, 1
	v_mov_b32_e32 v2, s16
	v_mov_b32_e32 v3, s17
	ds_write_b32 v1, v2
	ds_write_b32 v1, v3 offset:4
.Lgb0_have:
	s_add_u32 s19, s18, 1
	s_lshl_b32 s20, s15, 8
	v_mov_b32_e32 v2, s19
	s_add_u32 s20, s20, 0x1400
	ds_write_b32 v1, v2 offset:8
	v_mov_b32_e32 v5, s20
	v_mov_b32_e32 v6, 1
	global_atomic_add v7, v5, v6, s[12:13] sc0
	s_waitcnt vmcnt(0) lgkmcnt(0)
	v_readfirstlane_b32 s21, v7
	s_mul_i32 s22, s19, s16
	s_add_u32 s21, s21, 1
	s_cmp_lg_u32 s21, s22
	s_cbranch_scc1 .Lgb0_wait
	buffer_wbl2 sc1
	v_mov_b32_e32 v5, 0x3400
	s_waitcnt vmcnt(0) lgkmcnt(0)
	global_atomic_add v7, v5, v6, s[12:13] sc0
	s_waitcnt vmcnt(0)
	v_readfirstlane_b32 s21, v7
	s_mul_i32 s22, s19, s17
	s_add_u32 s21, s21, 1
	s_cmp_lg_u32 s21, s22
	s_cbranch_scc1 .Lgb0_wait
	v_mov_b32_e32 v5, 0x2400
	s_nop 0
	global_atomic_add v5, v6, s[12:13]
	global_atomic_add v5, v6, s[12:13] offset:256
	global_atomic_add v5, v6, s[12:13] offset:512
	global_atomic_add v5, v6, s[12:13] offset:768
	global_atomic_add v5, v6, s[12:13] offset:1024
	global_atomic_add v5, v6, s[12:13] offset:1280
	global_atomic_add v5, v6, s[12:13] offset:1536
	global_atomic_add v5, v6, s[12:13] offset:1792
	global_atomic_add v5, v6, s[12:13] offset:2048
	global_atomic_add v5, v6, s[12:13] offset:2304
	global_atomic_add v5, v6, s[12:13] offset:2560
	global_atomic_add v5, v6, s[12:13] offset:2816
	global_atomic_add v5, v6, s[12:13] offset:3072
	global_atomic_add v5, v6, s[12:13] offset:3328
	global_atomic_add v5, v6, s[12:13] offset:3584
	global_atomic_add v5, v6, s[12:13] offset:3840
.Lgb0_wait:
	s_lshl_b32 s20, s15, 8
	s_add_u32 s20, s20, 0x2400
	v_mov_b32_e32 v5, s20
	s_mov_b32 s23, 0
.Lgb0_spin:
	global_load_dword v7, v5, s[12:13] sc1
	s_waitcnt vmcnt(0)
	v_readfirstlane_b32 s21, v7
	s_cmp_lg_u32 s21, s18
	s_cbranch_scc1 .Lgb0_rel
	s_sleep 1
	s_add_u32 s23, s23, 1
	s_cmp_lt_u32 s23, 0x100000
	s_cbranch_scc1 .Lgb0_spin
.Lgb0_rel:
	buffer_inv sc1
	s_waitcnt vmcnt(0)
	s_mov_b64 exec, s[10:11]
.Lgb0_close:
	s_barrier

.LBB0_325:
	v_readlane_b32 s0, v254, 2
	v_readlane_b32 s1, v254, 3
	s_cmp_gt_i32 s1, 2
	s_cselect_b64 s[4:5], -1, 0
	s_and_b64 s[6:7], s[6:7], s[4:5]
	s_andn2_b64 vcc, exec, s[6:7]
	s_cbranch_vccnz .LBB0_375
	s_waitcnt vmcnt(0) lgkmcnt(0)
	s_barrier
	v_readfirstlane_b32 s0, v0
	s_lshr_b32 s0, s0, 6
	s_cmp_lg_u32 s0, 0
	s_cbranch_scc1 .Lgb1_close
	s_mov_b64 s[10:11], exec
	s_mov_b64 exec, 1
	v_readlane_b32 s12, v254, 36
	v_readlane_b32 s13, v254, 37
	v_readlane_b32 s14, v254, 38
	v_readlane_b32 s15, v254, 39
	s_nop 1
	v_mov_b32_e32 v1, s14
	ds_read_b32 v2, v1
	ds_read_b32 v3, v1 offset:4
	ds_read_b32 v4, v1 offset:8
	s_waitcnt lgkmcnt(0)
	v_readfirstlane_b32 s16, v2
	v_readfirstlane_b32 s17, v3
	v_readfirstlane_b32 s18, v4
	s_cmp_lg_u32 s16, 0
	s_cbranch_scc1 .Lgb1_have
	v_readlane_b32 s0, v254, 0
	v_readlane_b32 s1, v254, 1
	s_nop 4
	s_load_dwordx2 s[20:21], s[0:1], 0xe8
	s_load_dword s22, s[0:1], 0xf0
	v_mov_b32_e32 v5, 0
	v_mov_b32_e32 v6, 0x1000
	s_mov_b32 s19, 0
	s_waitcnt lgkmcnt(0)
	s_mul_i32 s20, s20, s21
	s_mul_i32 s20, s20, s22

.LBB0_604:
	v_readlane_b32 s0, v254, 2
	v_readlane_b32 s1, v254, 3
	s_cmp_gt_i32 s1, 3
	s_cselect_b64 s[4:5], -1, 0
	s_and_b64 s[6:7], s[40:41], s[4:5]
	s_andn2_b64 vcc, exec, s[6:7]
	s_cbranch_vccnz .LBB0_654
	s_waitcnt vmcnt(0) lgkmcnt(0)
	s_barrier
	v_readfirstlane_b32 s0, v0
	s_lshr_b32 s0, s0, 6
	s_cmp_lg_u32 s0, 0
	s_cbranch_scc1 .Lgb2_close
	s_mov_b64 s[10:11], exec
	s_mov_b64 exec, 1
	v_readlane_b32 s12, v254, 36
	v_readlane_b32 s13, v254, 37
	v_readlane_b32 s14, v254, 38
	v_readlane_b32 s15, v254, 39
	s_nop 1
	v_mov_b32_e32 v1, s14
	ds_read_b32 v2, v1
	ds_read_b32 v3, v1 offset:4
	ds_read_b32 v4, v1 offset:8
	s_waitcnt lgkmcnt(0)
	v_readfirstlane_b32 s16, v2
	v_readfirstlane_b32 s17, v3
	v_readfirstlane_b32 s18, v4
	s_cmp_lg_u32 s16, 0
	s_cbranch_scc1 .Lgb2_have
	v_readlane_b32 s0, v254, 0
	v_readlane_b32 s1, v254, 1
	s_nop 4
	s_load_dwordx2 s[20:21], s[0:1], 0xe8
	s_load_dword s22, s[0:1], 0xf0
	v_mov_b32_e32 v5, 0
	v_mov_b32_e32 v6, 0x1000
	s_mov_b32 s19, 0
	s_waitcnt lgkmcnt(0)
	s_mul_i32 s20, s20, s21
	s_mul_i32 s20, s20, s22

.LBB0_681:
	v_readlane_b32 s28, v254, 16
	v_readlane_b32 s29, v254, 17
	s_waitcnt vmcnt(0)
	v_lshrrev_b32_e32 v6, 4, v0
	v_and_b32_e32 v34, 63, v0
	v_lshlrev_b32_e32 v2, 2, v0
	v_mov_b32_e32 v3, 0
	v_lshrrev_b32_e32 v11, 6, v0
	v_mul_u32_u24_e32 v12, 0x210, v34
	v_lshl_add_u32 v11, v11, 1, v12
	s_mov_b64 s[4:5], 0
	s_nop 1
	global_load_dword v40, v2, s[28:29]
	global_load_dword v41, v2, s[28:29] offset:2048
	s_add_u32 s28, s28, 0x1000
	s_addc_u32 s29, s29, 0
	global_load_dword v42, v2, s[28:29]
	global_load_dword v43, v2, s[28:29] offset:2048
	s_add_u32 s28, s28, 0x1000
	s_addc_u32 s29, s29, 0
	global_load_dword v44, v2, s[28:29]
	global_load_dword v45, v2, s[28:29] offset:2048
	s_add_u32 s28, s28, 0x1000
	s_addc_u32 s29, s29, 0
	global_load_dword v46, v2, s[28:29]
	global_load_dword v47, v2, s[28:29] offset:2048
	s_add_u32 s28, s28, 0x1000
	s_addc_u32 s29, s29, 0
	global_load_dword v48, v2, s[28:29]
	global_load_dword v49, v2, s[28:29] offset:2048
	s_add_u32 s28, s28, 0x1000
	s_addc_u32 s29, s29, 0
	global_load_dword v50, v2, s[28:29]
	global_load_dword v51, v2, s[28:29] offset:2048
	s_add_u32 s28, s28, 0x1000
	s_addc_u32 s29, s29, 0
	global_load_dword v52, v2, s[28:29]
	global_load_dword v53, v2, s[28:29] offset:2048
	s_add_u32 s28, s28, 0x1000
	s_addc_u32 s29, s29, 0
	global_load_dword v54, v2, s[28:29]
	global_load_dword v55, v2, s[28:29] offset:2048
	s_add_u32 s28, s28, 0x1000
	s_addc_u32 s29, s29, 0
	global_load_dword v56, v2, s[28:29]
	global_load_dword v57, v2, s[28:29] offset:2048
	s_add_u32 s28, s28, 0x1000
	s_addc_u32 s29, s29, 0
	global_load_dword v58, v2, s[28:29]
	global_load_dword v59, v2, s[28:29] offset:2048
	s_add_u32 s28, s28, 0x1000
	s_addc_u32 s29, s29, 0
	global_load_dword v60, v2, s[28:29]
	global_load_dword v61, v2, s[28:29] offset:2048
	s_add_u32 s28, s28, 0x1000
	s_addc_u32 s29, s29, 0
	global_load_dword v62, v2, s[28:29]
	global_load_dword v63, v2, s[28:29] offset:2048
	s_add_u32 s28, s28, 0x1000
	s_addc_u32 s29, s29, 0
	global_load_dword v64, v2, s[28:29]
	global_load_dword v65, v2, s[28:29] offset:2048
	s_add_u32 s28, s28, 0x1000
	s_addc_u32 s29, s29, 0
	global_load_dword v66, v2, s[28:29]
	global_load_dword v67, v2, s[28:29] offset:2048
	s_add_u32 s28, s28, 0x1000
	s_addc_u32 s29, s29, 0
	global_load_dword v68, v2, s[28:29]
	global_load_dword v69, v2, s[28:29] offset:2048
	s_add_u32 s28, s28, 0x1000
	s_addc_u32 s29, s29, 0
	global_load_dword v70, v2, s[28:29]
	global_load_dword v71, v2, s[28:29] offset:2048
	s_add_u32 s28, s28, 0x1000
	s_addc_u32 s29, s29, 0
	global_load_dword v72, v2, s[28:29]
	global_load_dword v73, v2, s[28:29] offset:2048
	s_add_u32 s28, s28, 0x1000
	s_addc_u32 s29, s29, 0
	global_load_dword v74, v2, s[28:29]
	global_load_dword v75, v2, s[28:29] offset:2048
	s_add_u32 s28, s28, 0x1000
	s_addc_u32 s29, s29, 0
	global_load_dword v76, v2, s[28:29]
	global_load_dword v77, v2, s[28:29] offset:2048
	s_add_u32 s28, s28, 0x1000
	s_addc_u32 s29, s29, 0
	global_load_dword v78, v2, s[28:29]
	global_load_dword v79, v2, s[28:29] offset:2048
	s_add_u32 s28, s28, 0x1000
	s_addc_u32 s29, s29, 0
	global_load_dword v80, v2, s[28:29]
	global_load_dword v81, v2, s[28:29] offset:2048
	s_add_u32 s28, s28, 0x1000
	s_addc_u32 s29, s29, 0
	global_load_dword v82, v2, s[28:29]
	global_load_dword v83, v2, s[28:29] offset:2048
	s_add_u32 s28, s28, 0x1000
	s_addc_u32 s29, s29, 0
	global_load_dword v84, v2, s[28:29]
	global_load_dword v85, v2, s[28:29] offset:2048
	s_add_u32 s28, s28, 0x1000
	s_addc_u32 s29, s29, 0
	global_load_dword v86, v2, s[28:29]
	global_load_dword v87, v2, s[28:29] offset:2048
	s_add_u32 s28, s28, 0x1000
	s_addc_u32 s29, s29, 0
	global_load_dword v88, v2, s[28:29]
	global_load_dword v89, v2, s[28:29] offset:2048
	s_add_u32 s28, s28, 0x1000
	s_addc_u32 s29, s29, 0
	global_load_dword v90, v2, s[28:29]
	global_load_dword v91, v2, s[28:29] offset:2048
	s_add_u32 s28, s28, 0x1000
	s_addc_u32 s29, s29, 0
	global_load_dword v92, v2, s[28:29]
	global_load_dword v93, v2, s[28:29] offset:2048
	s_add_u32 s28, s28, 0x1000
	s_addc_u32 s29, s29, 0
	global_load_dword v94, v2, s[28:29]
	global_load_dword v95, v2, s[28:29] offset:2048
	s_add_u32 s28, s28, 0x1000
	s_addc_u32 s29, s29, 0
	global_load_dword v96, v2, s[28:29]
	global_load_dword v97, v2, s[28:29] offset:2048
	s_add_u32 s28, s28, 0x1000
	s_addc_u32 s29, s29, 0
	global_load_dword v98, v2, s[28:29]
	global_load_dword v99, v2, s[28:29] offset:2048
	s_add_u32 s28, s28, 0x1000
	s_addc_u32 s29, s29, 0
	global_load_dword v100, v2, s[28:29]
	global_load_dword v101, v2, s[28:29] offset:2048
	s_add_u32 s28, s28, 0x1000
	s_addc_u32 s29, s29, 0
	global_load_dword v102, v2, s[28:29]
	global_load_dword v103, v2, s[28:29] offset:2048
	s_waitcnt vmcnt(63)
	v_cvt_pk_bf16_f32 v40, v40, v3
	ds_write_b16 v11, v40
	s_waitcnt vmcnt(62)
	v_cvt_pk_bf16_f32 v41, v41, v3
	ds_write_b16 v11, v41 offset:16
	s_waitcnt vmcnt(61)
	v_cvt_pk_bf16_f32 v42, v42, v3
	ds_write_b16 v11, v42 offset:32
	s_waitcnt vmcnt(60)
	v_cvt_pk_bf16_f32 v43, v43, v3
	ds_write_b16 v11, v43 offset:48
	s_waitcnt vmcnt(59)
	v_cvt_pk_bf16_f32 v44, v44, v3
	ds_write_b16 v11, v44 offset:64
	s_waitcnt vmcnt(58)
	v_cvt_pk_bf16_f32 v45, v45, v3
	ds_write_b16 v11, v45 offset:80
	s_waitcnt vmcnt(57)
	v_cvt_pk_bf16_f32 v46, v46, v3
	ds_write_b16 v11, v46 offset:96
	s_waitcnt vmcnt(56)
	v_cvt_pk_bf16_f32 v47, v47, v3
	ds_write_b16 v11, v47 offset:112
	s_waitcnt vmcnt(55)
	v_cvt_pk_bf16_f32 v48, v48, v3
	ds_write_b16 v11, v48 offset:128
	s_waitcnt vmcnt(54)
	v_cvt_pk_bf16_f32 v49, v49, v3
	ds_write_b16 v11, v49 offset:144
	s_waitcnt vmcnt(53)
	v_cvt_pk_bf16_f32 v50, v50, v3
	ds_write_b16 v11, v50 offset:160
	s_waitcnt vmcnt(52)
	v_cvt_pk_bf16_f32 v51, v51, v3
	ds_write_b16 v11, v51 offset:176
	s_waitcnt vmcnt(51)
	v_cvt_pk_bf16_f32 v52, v52, v3
	ds_write_b16 v11, v52 offset:192
	s_waitcnt vmcnt(50)
	v_cvt_pk_bf16_f32 v53, v53, v3
	ds_write_b16 v11, v53 offset:208
	s_waitcnt vmcnt(49)
	v_cvt_pk_bf16_f32 v54, v54, v3
	ds_write_b16 v11, v54 offset:224
	s_waitcnt vmcnt(48)
	v_cvt_pk_bf16_f32 v55, v55, v3
	ds_write_b16 v11, v55 offset:240
	s_waitcnt vmcnt(47)
	v_cvt_pk_bf16_f32 v56, v56, v3
	ds_write_b16 v11, v56 offset:256
	s_waitcnt vmcnt(46)
	v_cvt_pk_bf16_f32 v57, v57, v3
	ds_write_b16 v11, v57 offset:272
	s_waitcnt vmcnt(45)
	v_cvt_pk_bf16_f32 v58, v58, v3
	ds_write_b16 v11, v58 offset:288
	s_waitcnt vmcnt(44)
	v_cvt_pk_bf16_f32 v59, v59, v3
	ds_write_b16 v11, v59 offset:304
	s_waitcnt vmcnt(43)
	v_cvt_pk_bf16_f32 v60, v60, v3
	ds_write_b16 v11, v60 offset:320
	s_waitcnt vmcnt(42)
	v_cvt_pk_bf16_f32 v61, v61, v3
	ds_write_b16 v11, v61 offset:336
	s_waitcnt vmcnt(41)
	v_cvt_pk_bf16_f32 v62, v62, v3
	ds_write_b16 v11, v62 offset:352
	s_waitcnt vmcnt(40)
	v_cvt_pk_bf16_f32 v63, v63, v3
	ds_write_b16 v11, v63 offset:368
	s_waitcnt vmcnt(39)
	v_cvt_pk_bf16_f32 v64, v64, v3
	ds_write_b16 v11, v64 offset:384
	s_waitcnt vmcnt(38)
	v_cvt_pk_bf16_f32 v65, v65, v3
	ds_write_b16 v11, v65 offset:400
	s_waitcnt vmcnt(37)
	v_cvt_pk_bf16_f32 v66, v66, v3
	ds_write_b16 v11, v66 offset:416
	s_waitcnt vmcnt(36)
	v_cvt_pk_bf16_f32 v67, v67, v3
	ds_write_b16 v11, v67 offset:432
	s_waitcnt vmcnt(35)
	v_cvt_pk_bf16_f32 v68, v68, v3
	ds_write_b16 v11, v68 offset:448
	s_waitcnt vmcnt(34)
	v_cvt_pk_bf16_f32 v69, v69, v3
	ds_write_b16 v11, v69 offset:464
	s_waitcnt vmcnt(33)
	v_cvt_pk_bf16_f32 v70, v70, v3
	ds_write_b16 v11, v70 offset:480
	s_waitcnt vmcnt(32)
	v_cvt_pk_bf16_f32 v71, v71, v3
	ds_write_b16 v11, v71 offset:496
	s_waitcnt vmcnt(31)
	v_cvt_pk_bf16_f32 v72, v72, v3
	ds_write_b16 v11, v72 offset:33792
	s_waitcnt vmcnt(30)
	v_cvt_pk_bf16_f32 v73, v73, v3
	ds_write_b16 v11, v73 offset:33808
	s_waitcnt vmcnt(29)
	v_cvt_pk_bf16_f32 v74, v74, v3
	ds_write_b16 v11, v74 offset:33824
	s_waitcnt vmcnt(28)
	v_cvt_pk_bf16_f32 v75, v75, v3
	ds_write_b16 v11, v75 offset:33840
	s_waitcnt vmcnt(27)
	v_cvt_pk_bf16_f32 v76, v76, v3
	ds_write_b16 v11, v76 offset:33856
	s_waitcnt vmcnt(26)
	v_cvt_pk_bf16_f32 v77, v77, v3
	ds_write_b16 v11, v77 offset:33872
	s_waitcnt vmcnt(25)
	v_cvt_pk_bf16_f32 v78, v78, v3
	ds_write_b16 v11, v78 offset:33888
	s_waitcnt vmcnt(24)
	v_cvt_pk_bf16_f32 v79, v79, v3
	ds_write_b16 v11, v79 offset:33904
	s_waitcnt vmcnt(23)
	v_cvt_pk_bf16_f32 v80, v80, v3
	ds_write_b16 v11, v80 offset:33920
	s_waitcnt vmcnt(22)
	v_cvt_pk_bf16_f32 v81, v81, v3
	ds_write_b16 v11, v81 offset:33936
	s_waitcnt vmcnt(21)
	v_cvt_pk_bf16_f32 v82, v82, v3
	ds_write_b16 v11, v82 offset:33952
	s_waitcnt vmcnt(20)
	v_cvt_pk_bf16_f32 v83, v83, v3
	ds_write_b16 v11, v83 offset:33968
	s_waitcnt vmcnt(19)
	v_cvt_pk_bf16_f32 v84, v84, v3
	ds_write_b16 v11, v84 offset:33984
	s_waitcnt vmcnt(18)
	v_cvt_pk_bf16_f32 v85, v85, v3
	ds_write_b16 v11, v85 offset:34000
	s_waitcnt vmcnt(17)
	v_cvt_pk_bf16_f32 v86, v86, v3
	ds_write_b16 v11, v86 offset:34016
	s_waitcnt vmcnt(16)
	v_cvt_pk_bf16_f32 v87, v87, v3
	ds_write_b16 v11, v87 offset:34032
	s_waitcnt vmcnt(15)
	v_cvt_pk_bf16_f32 v88, v88, v3
	ds_write_b16 v11, v88 offset:34048
	s_waitcnt vmcnt(14)
	v_cvt_pk_bf16_f32 v89, v89, v3
	ds_write_b16 v11, v89 offset:34064
	s_waitcnt vmcnt(13)
	v_cvt_pk_bf16_f32 v90, v90, v3
	ds_write_b16 v11, v90 offset:34080
	s_waitcnt vmcnt(12)
	v_cvt_pk_bf16_f32 v91, v91, v3
	ds_write_b16 v11, v91 offset:34096
	s_waitcnt vmcnt(11)
	v_cvt_pk_bf16_f32 v92, v92, v3
	ds_write_b16 v11, v92 offset:34112
	s_waitcnt vmcnt(10)
	v_cvt_pk_bf16_f32 v93, v93, v3
	ds_write_b16 v11, v93 offset:34128
	s_waitcnt vmcnt(9)
	v_cvt_pk_bf16_f32 v94, v94, v3
	ds_write_b16 v11, v94 offset:34144
	s_waitcnt vmcnt(8)
	v_cvt_pk_bf16_f32 v95, v95, v3
	ds_write_b16 v11, v95 offset:34160
	s_waitcnt vmcnt(7)
	v_cvt_pk_bf16_f32 v96, v96, v3
	ds_write_b16 v11, v96 offset:34176
	s_waitcnt vmcnt(6)
	v_cvt_pk_bf16_f32 v97, v97, v3
	ds_write_b16 v11, v97 offset:34192
	s_waitcnt vmcnt(5)
	v_cvt_pk_bf16_f32 v98, v98, v3
	ds_write_b16 v11, v98 offset:34208
	s_waitcnt vmcnt(4)
	v_cvt_pk_bf16_f32 v99, v99, v3
	ds_write_b16 v11, v99 offset:34224
	s_waitcnt vmcnt(3)
	v_cvt_pk_bf16_f32 v100, v100, v3
	ds_write_b16 v11, v100 offset:34240
	s_waitcnt vmcnt(2)
	v_cvt_pk_bf16_f32 v101, v101, v3
	ds_write_b16 v11, v101 offset:34256
	s_waitcnt vmcnt(1)
	v_cvt_pk_bf16_f32 v102, v102, v3
	ds_write_b16 v11, v102 offset:34272
	s_waitcnt vmcnt(0)
	v_cvt_pk_bf16_f32 v103, v103, v3
	ds_write_b16 v11, v103 offset:34288
	s_or_b64 exec, exec, s[4:5]
	v_readfirstlane_b32 s4, v0
	s_andn2_b64 vcc, exec, s[12:13]
	s_waitcnt lgkmcnt(0)
	s_barrier
	s_cbranch_vccnz .LBB0_693
	s_lshr_b32 s0, s4, 6
	s_add_u32 s20, s54, 0x4eeaa800
	s_addc_u32 s21, s55, 0
	s_cmpk_lt_u32 s4, 0x400
	v_lshlrev_b32_e32 v3, 3, v1
	s_cselect_b64 s[12:13], -1, 0
	s_and_b32 s1, s4, 64
	v_and_b32_e32 v3, 16, v3
	v_lshlrev_b32_e32 v16, 4, v1
	v_and_or_b32 v1, v0, 12, v1
	v_or3_b32 v5, v3, s1, v130
	v_lshlrev_b32_e32 v2, 5, v1
	v_lshlrev_b32_e32 v1, 2, v6
	v_lshlrev_b32_e32 v6, 3, v5
	v_or_b32_e32 v5, 32, v3
	v_or3_b32 v7, v5, s1, v130
	s_bitset1_b32 s1, 7
	v_or3_b32 v3, v3, s1, v130
	v_lshlrev_b32_e32 v10, 3, v3
	v_or3_b32 v3, v5, s1, v130
	v_mov_b32_e32 v17, 0
	v_and_b32_e32 v4, 4, v1
	v_lshlrev_b32_e32 v8, 3, v7
	v_lshlrev_b32_e32 v12, 3, v3
	v_cndmask_b32_e64 v3, 0, 1, s[12:13]
	v_lshl_add_u64 v[18:19], s[10:11], 0, v[16:17]
	s_mov_b32 s11, 0
	v_add_u32_e32 v35, 0, v16
	v_and_b32_e32 v1, 3, v0
	s_add_i32 s22, s0, -8
	s_lshl_b32 s23, s0, 2
	s_lshl_b32 s24, s0, 4
	v_cmp_ne_u32_e64 s[4:5], 1, v3
	s_movk_i32 s25, 0x210
	v_lshlrev_b32_e32 v20, 1, v2
	s_mov_b64 s[12:13], 0x1000
	s_movk_i32 s26, 0x1000
	v_lshlrev_b32_e32 v16, 1, v4
	v_lshlrev_b32_e32 v22, 1, v6
	v_lshlrev_b32_e32 v24, 1, v8
	v_lshlrev_b32_e32 v26, 1, v10
	v_lshlrev_b32_e32 v28, 1, v12
	s_mov_b32 s27, s2
	s_branch .LBB0_686

.LBB0_693:
	s_cmp_lt_u32 s2, 8
	s_barrier
	s_cbranch_scc1 .LBB0_950
	s_mov_b64 exec, -1
	v_readlane_b32 s0, v254, 0
	v_readlane_b32 s1, v254, 1
	s_nop 4
	s_load_dwordx2 s[56:57], s[0:1], 0xa8
	s_load_dwordx2 s[58:59], s[0:1], 0xc0
	s_load_dwordx2 s[60:61], s[0:1], 0x88
	s_load_dwordx2 s[62:63], s[0:1], 0x78
	s_load_dwordx2 s[64:65], s[0:1], 0x80
	s_load_dwordx2 s[66:67], s[0:1], 0x90
	s_load_dwordx2 s[68:69], s[0:1], 0xa0
	s_load_dwordx2 s[70:71], s[0:1], 0x48
	s_load_dwordx2 s[72:73], s[0:1], 0xd8
	s_load_dword s3, s[0:1], 0xe8
	v_readfirstlane_b32 s4, v0
	v_and_b32_e32 v7, 63, v0
	s_lshr_b32 s4, s4, 6
	v_lshrrev_b32_e32 v1, 3, v7
	v_and_b32_e32 v2, 7, v7
	s_lshl_b32 s5, s4, 14
	v_lshlrev_b32_e32 v5, 5, v2
	s_movk_i32 s14, 0x420
	v_mul_u32_u24_e32 v4, s14, v2
	v_lshlrev_b32_e32 v2, 4, v2
	s_movk_i32 s14, 0x84
	v_mad_u32_u24 v3, v1, s14, v2
	v_lshl_add_u32 v4, v1, 2, v4
	v_add_u32_e32 v3, s5, v3
	v_add_u32_e32 v4, s5, v4
	v_mov_b32_e32 v124, v3
	v_add_u32_e32 v125, 1056, v3
	v_add_u32_e32 v126, 2112, v3
	v_add_u32_e32 v127, 3168, v3
	v_add_u32_e32 v128, 4224, v3
	v_add_u32_e32 v129, 5280, v3
	v_add_u32_e32 v130, 6336, v3
	v_add_u32_e32 v131, 7392, v3
	s_waitcnt lgkmcnt(0)
	s_sub_u32 s5, s2, 8
	s_lshl_b32 s5, s5, 3
	s_add_u32 s20, s5, s4
	s_sub_u32 s21, s3, 8
	s_lshl_b32 s21, s21, 3
	s_cmp_ge_u32 s20, 0x5600
	s_cbranch_scc1 .LBB0_949
	s_mov_b32 s26, s20
	s_cmp_lt_u32 s26, 0x2c00
	s_cbranch_scc1 .Ltrp3_i1_s0
	s_sub_u32 s26, s26, 0x2c00
	s_cmp_lt_u32 s26, 0x1600
	s_cbranch_scc1 .Ltrp3_i1_s1
	s_sub_u32 s26, s26, 0x1600
	s_cmp_lt_u32 s26, 0x800
	s_cbranch_scc1 .Ltrp3_i1_s2
	s_sub_u32 s26, s26, 0x800
	s_cmp_lt_u32 s26, 0x400
	s_cbranch_scc1 .Ltrp3_i1_s3
	s_sub_u32 s26, s26, 0x400
	s_cmp_lt_u32 s26, 0x400
	s_cbranch_scc1 .Ltrp3_i1_s4
	s_sub_u32 s26, s26, 0x400
	s_cmp_lt_u32 s26, 0x200
	s_cbranch_scc1 .Ltrp3_i1_s5
	s_sub_u32 s26, s26, 0x200
	s_branch .Ltrp3_i1_s6

.LBB0_950:
	v_readlane_b32 s0, v254, 2
	v_readlane_b32 s1, v254, 3
	s_cmp_gt_i32 s1, 4
	s_cselect_b64 s[4:5], -1, 0
	s_and_b64 s[6:7], s[6:7], s[4:5]
	v_readlane_b32 s64, v254, 48
	s_andn2_b64 vcc, exec, s[6:7]
	v_readlane_b32 s66, v254, 50
	v_readlane_b32 s67, v254, 51
	v_readlane_b32 s76, v254, 60
	v_readlane_b32 s77, v254, 61
	v_readlane_b32 s78, v254, 62
	v_readlane_b32 s79, v254, 63
	v_readlane_b32 s65, v254, 49
	v_readlane_b32 s68, v254, 52
	v_readlane_b32 s69, v254, 53
	v_readlane_b32 s70, v254, 54
	v_readlane_b32 s71, v254, 55
	v_readlane_b32 s72, v254, 56
	v_readlane_b32 s73, v254, 57
	v_readlane_b32 s74, v254, 58
	v_readlane_b32 s75, v254, 59
	s_cbranch_vccnz .LBB0_1000
	s_waitcnt vmcnt(0) lgkmcnt(0)
	s_barrier
	v_readfirstlane_b32 s0, v0
	s_lshr_b32 s0, s0, 6
	s_cmp_lg_u32 s0, 0
	s_cbranch_scc1 .Lgb3_close
	s_mov_b64 s[10:11], exec
	s_mov_b64 exec, 1
	v_readlane_b32 s12, v254, 36
	v_readlane_b32 s13, v254, 37
	v_readlane_b32 s14, v254, 38
	v_readlane_b32 s15, v254, 39
	s_nop 1
	v_mov_b32_e32 v1, s14
	ds_read_b32 v2, v1
	ds_read_b32 v3, v1 offset:4
	ds_read_b32 v4, v1 offset:8
	s_waitcnt lgkmcnt(0)
	v_readfirstlane_b32 s16, v2
	v_readfirstlane_b32 s17, v3
	v_readfirstlane_b32 s18, v4
	s_cmp_lg_u32 s16, 0
	s_cbranch_scc1 .Lgb3_have
	v_readlane_b32 s0, v254, 0
	v_readlane_b32 s1, v254, 1
	s_nop 4
	s_load_dwordx2 s[20:21], s[0:1], 0xe8
	s_load_dword s22, s[0:1], 0xf0
	v_mov_b32_e32 v5, 0
	v_mov_b32_e32 v6, 0x1000
	s_mov_b32 s19, 0
	s_waitcnt lgkmcnt(0)
	s_mul_i32 s20, s20, s21
	s_mul_i32 s20, s20, s22

.LBB0_1313:
	v_readlane_b32 s0, v254, 2
	v_readlane_b32 s1, v254, 3
	s_cmp_gt_i32 s1, 5
	s_cselect_b64 s[4:5], -1, 0
	s_and_b64 s[6:7], s[46:47], s[4:5]
	s_andn2_b64 vcc, exec, s[6:7]
	s_cbranch_vccnz .LBB0_1363
	s_waitcnt vmcnt(0) lgkmcnt(0)
	s_barrier
	v_readfirstlane_b32 s0, v0
	s_lshr_b32 s0, s0, 6
	s_cmp_lg_u32 s0, 0
	s_cbranch_scc1 .Lgb4_close
	s_mov_b64 s[10:11], exec
	s_mov_b64 exec, 1
	v_readlane_b32 s12, v254, 36
	v_readlane_b32 s13, v254, 37
	v_readlane_b32 s14, v254, 38
	v_readlane_b32 s15, v254, 39
	s_nop 1
	v_mov_b32_e32 v1, s14
	ds_read_b32 v2, v1
	ds_read_b32 v3, v1 offset:4
	ds_read_b32 v4, v1 offset:8
	s_waitcnt lgkmcnt(0)
	v_readfirstlane_b32 s16, v2
	v_readfirstlane_b32 s17, v3
	v_readfirstlane_b32 s18, v4
	s_cmp_lg_u32 s16, 0
	s_cbranch_scc1 .Lgb4_have
	v_readlane_b32 s0, v254, 0
	v_readlane_b32 s1, v254, 1
	s_nop 4
	s_load_dwordx2 s[20:21], s[0:1], 0xe8
	s_load_dword s22, s[0:1], 0xf0
	v_mov_b32_e32 v5, 0
	v_mov_b32_e32 v6, 0x1000
	s_mov_b32 s19, 0
	s_waitcnt lgkmcnt(0)
	s_mul_i32 s20, s20, s21
	s_mul_i32 s20, s20, s22

.LBB0_1379:
	s_cmp_le_u32 s30, s59
	s_cselect_b64 s[44:45], -1, 0
	s_cmp_gt_u32 s30, s59
	s_cbranch_scc1 .LBB0_1381
	v_add_co_u32_e32 v4, vcc, 0xffff7000, v196
	s_nop 1
	v_addc_co_u32_e32 v5, vcc, -1, v197, vcc
	global_load_dwordx4 v[90:93], v[4:5], off offset:-3072
	global_load_dwordx4 v[86:89], v[4:5], off offset:-2048
	global_load_dwordx4 v[82:85], v[4:5], off offset:-1024
	global_load_dwordx4 v[78:81], v[4:5], off
	v_add_co_u32_e32 v4, vcc, 0xffff8000, v196
	s_nop 1
	v_addc_co_u32_e32 v5, vcc, -1, v197, vcc
	global_load_dwordx4 v[106:109], v[4:5], off offset:-3072
	global_load_dwordx4 v[102:105], v[4:5], off offset:-2048
	global_load_dwordx4 v[98:101], v[4:5], off offset:-1024
	global_load_dwordx4 v[94:97], v[4:5], off
	s_waitcnt vmcnt(16)
	s_branch .Lp6w_0

.Lp6w_0:
	s_cmp_ge_u32 s61, s60
	s_cselect_b64 s[12:13], -1, 0
	s_add_i32 s0, s61, 31
	s_cmp_le_u32 s0, s56
	s_cselect_b64 s[14:15], -1, 0
	s_and_b64 s[14:15], s[12:13], s[14:15]
	s_mov_b64 s[12:13], -1
	s_and_b64 vcc, exec, s[14:15]
	s_cbranch_vccnz .LBB0_1385
	v_add_u32_e32 v2, s61, v164
	v_add_u32_e32 v4, 0x1ff, v2
	s_nop 0
	v_mfma_f32_16x16x32_bf16 v[130:133], v[14:17], v[6:9], 0
	v_cmp_ge_u32_e32 vcc, v4, v195
	v_cmp_le_u32_e64 s[12:13], v2, v195
	v_add_u32_e32 v4, 0x200, v2
	s_and_b64 s[16:17], s[12:13], vcc
	v_cmp_lt_u32_e32 vcc, v4, v195
	v_cmp_ge_u32_e64 s[12:13], v2, v195
	v_add_u32_e32 v4, 2, v2
	v_add_u32_e32 v5, 0x201, v2
	v_mfma_f32_16x16x32_bf16 v[134:137], v[18:21], v[6:9], 0
	s_or_b64 vcc, s[12:13], vcc
	v_cmp_lt_u32_e64 s[12:13], v5, v195
	v_cmp_gt_u32_e64 s[14:15], v4, v195
	v_add_u32_e32 v4, 3, v2
	v_add_u32_e32 v5, 0x202, v2
	s_or_b64 s[12:13], s[14:15], s[12:13]
	v_cmp_lt_u32_e64 s[14:15], v5, v195
	v_cmp_gt_u32_e64 s[18:19], v4, v195
	v_add_u32_e32 v4, 16, v2
	v_add_u32_e32 v5, 0x20f, v2
	s_nop 0
	v_mfma_f32_16x16x32_bf16 v[138:141], v[22:25], v[10:13], v[130:133]
	s_or_b64 s[14:15], s[18:19], s[14:15]
	v_cmp_lt_u32_e64 s[18:19], v5, v195
	v_cmp_gt_u32_e64 s[20:21], v4, v195
	v_add_u32_e32 v4, 17, v2
	v_add_u32_e32 v5, 0x210, v2
	s_or_b64 s[22:23], s[20:21], s[18:19]
	v_cmp_lt_u32_e64 s[18:19], v5, v195
	v_cmp_gt_u32_e64 s[20:21], v4, v195
	v_add_u32_e32 v4, 18, v2
	v_add_u32_e32 v5, 0x211, v2
	v_mfma_f32_16x16x32_bf16 v[142:145], v[26:29], v[10:13], v[134:137]
	s_or_b64 s[24:25], s[20:21], s[18:19]
	v_cmp_lt_u32_e64 s[18:19], v5, v195
	v_cmp_gt_u32_e64 s[20:21], v4, v195
	v_add_u32_e32 v4, 19, v2
	v_add_u32_e32 v2, 0x212, v2
	s_or_b64 s[20:21], s[20:21], s[18:19]
	v_cmp_lt_u32_e64 s[18:19], v2, v195
	v_cmp_gt_u32_e64 s[26:27], v4, v195
	v_cndmask_b32_e64 v133, v229, v138, s[16:17]
	v_cndmask_b32_e32 v135, v139, v229, vcc
	s_or_b64 s[18:19], s[26:27], s[18:19]
	v_cndmask_b32_e64 v156, v140, v229, s[12:13]
	v_cndmask_b32_e64 v157, v141, v229, s[14:15]
	v_max_f32_e32 v2, v135, v135
	v_max_f32_e32 v130, v133, v133
	v_cndmask_b32_e64 v132, v144, v229, s[20:21]
	v_cndmask_b32_e64 v134, v145, v229, s[18:19]
	v_max_f32_e32 v2, v130, v2
	v_max_f32_e32 v130, v157, v157
	v_max_f32_e32 v131, v156, v156
	v_max_f32_e32 v130, v131, v130
	v_max_f32_e32 v131, v134, v134
	v_max_f32_e32 v136, v132, v132
	v_cndmask_b32_e64 v4, v142, v229, s[22:23]
	v_cndmask_b32_e64 v5, v143, v229, s[24:25]
	v_max_f32_e32 v131, v136, v131
	v_max3_f32 v131, v4, v5, v131
	v_max3_f32 v159, v2, v130, v131
	v_add_f32_e32 v2, 0x41380000, v239
	v_cmp_le_f32_e32 vcc, v159, v2
	v_mov_b64_e32 v[138:139], v[128:129]
	v_mov_b64_e32 v[154:155], v[124:125]
	v_mov_b64_e32 v[150:151], v[120:121]
	v_mov_b64_e32 v[146:147], v[116:117]
	v_mov_b64_e32 v[142:143], v[112:113]
	s_cmp_lg_u64 vcc, exec
	v_mov_b64_e32 v[136:137], v[126:127]
	v_mov_b32_e32 v2, v239
	v_mov_b64_e32 v[152:153], v[122:123]
	v_mov_b64_e32 v[148:149], v[118:119]
	v_mov_b64_e32 v[144:145], v[114:115]
	v_mov_b64_e32 v[140:141], v[110:111]
	v_mov_b32_e32 v158, v240
	v_mov_b32_e32 v130, v126
	v_mov_b32_e32 v131, v127
	v_mov_b32_e32 v241, v128
	v_mov_b32_e32 v242, v129
	s_cbranch_scc0 .LBB0_1384
	v_mov_b32_e32 v2, v159
	s_nop 1
	v_permlane16_swap_b32_e32 v159, v2
	v_max_f32_e32 v2, v2, v2
	v_max_f32_e32 v130, v159, v159
	v_max_f32_e32 v2, v130, v2
	v_mov_b32_e32 v130, v2
	s_nop 1
	v_permlane32_swap_b32_e32 v2, v130
	v_max3_f32 v2, v239, v2, v130
	v_cmp_neq_f32_e32 vcc, s76, v2
	s_nop 1
	v_cndmask_b32_e32 v131, 0, v2, vcc
	v_sub_f32_e32 v130, v239, v131
	v_exp_f32_e32 v130, v130
	v_xor_b32_e32 v136, 0x80000000, v131
	v_mov_b32_e32 v137, v136
	v_mov_b32_e32 v138, v136
	v_mul_f32_e32 v158, v240, v130
	v_pk_mul_f32 v[142:143], v[112:113], v[130:131] op_sel_hi:[1,0]
	v_pk_mul_f32 v[140:141], v[110:111], v[130:131] op_sel_hi:[1,0]
	v_pk_mul_f32 v[146:147], v[116:117], v[130:131] op_sel_hi:[1,0]
	v_pk_mul_f32 v[144:145], v[114:115], v[130:131] op_sel_hi:[1,0]
	v_pk_mul_f32 v[150:151], v[120:121], v[130:131] op_sel_hi:[1,0]
	v_pk_mul_f32 v[148:149], v[118:119], v[130:131] op_sel_hi:[1,0]
	v_pk_mul_f32 v[154:155], v[124:125], v[130:131] op_sel_hi:[1,0]
	v_pk_mul_f32 v[152:153], v[122:123], v[130:131] op_sel_hi:[1,0]
	v_mov_b32_e32 v139, v136
	v_mov_b32_e32 v130, v136
	v_mov_b32_e32 v131, v136
	v_mov_b32_e32 v241, v136
	v_mov_b32_e32 v242, v136

.LBB0_1385:
	s_and_b64 vcc, exec, s[12:13]
	s_cbranch_vccz .LBB0_1392
	s_nop 0
	v_mfma_f32_16x16x32_bf16 v[130:133], v[14:17], v[6:9], v[126:129]
	v_cmp_eq_f32_e32 vcc, s76, v239
	s_nop 0
	v_mfma_f32_16x16x32_bf16 v[160:163], v[22:25], v[10:13], v[130:133]
	v_mfma_f32_16x16x32_bf16 v[130:133], v[18:21], v[6:9], v[126:129]
	v_mfma_f32_16x16x32_bf16 v[156:159], v[26:29], v[10:13], v[130:133]
	s_nop 5
	v_max_f32_e32 v2, v161, v161
	v_max_f32_e32 v4, v160, v160
	v_max_f32_e32 v2, v4, v2
	v_max_f32_e32 v4, v163, v163
	v_max_f32_e32 v5, v162, v162
	v_max_f32_e32 v4, v5, v4
	v_max_f32_e32 v5, v159, v159
	v_max_f32_e32 v130, v158, v158
	v_max_f32_e32 v5, v130, v5
	v_max3_f32 v5, v156, v157, v5
	v_max3_f32 v2, v2, v4, v5
	v_cndmask_b32_e32 v4, v230, v229, vcc
	v_cmp_le_f32_e32 vcc, v2, v4
	s_cmp_lg_u64 vcc, exec
	s_cbranch_scc0 .LBB0_1388
	v_sub_f32_e32 v2, v2, v126
	v_mov_b32_e32 v4, v2
	s_nop 1
	v_permlane16_swap_b32_e32 v2, v4
	v_max_f32_e32 v4, v4, v4
	v_max_f32_e32 v2, v2, v2
	v_max_f32_e32 v2, v2, v4
	v_mov_b32_e32 v4, v2
	s_nop 1
	v_permlane32_swap_b32_e32 v2, v4
	v_max3_f32 v2, v239, v2, v4
	v_cmp_neq_f32_e32 vcc, s76, v2
	s_mov_b64 s[12:13], 0
	s_nop 0
	v_cndmask_b32_e32 v5, 0, v2, vcc
	v_sub_f32_e32 v4, v239, v5
	v_exp_f32_e32 v132, v4
	v_xor_b32_e32 v130, 0x80000000, v5
	v_add_f32_e32 v5, v126, v5
	v_mov_b32_e32 v131, v130
	v_mul_f32_e32 v4, v240, v132
	v_pk_mul_f32 v[142:143], v[112:113], v[132:133] op_sel_hi:[1,0]
	v_pk_mul_f32 v[140:141], v[110:111], v[132:133] op_sel_hi:[1,0]
	v_pk_mul_f32 v[146:147], v[116:117], v[132:133] op_sel_hi:[1,0]
	v_pk_mul_f32 v[144:145], v[114:115], v[132:133] op_sel_hi:[1,0]
	v_pk_mul_f32 v[150:151], v[120:121], v[132:133] op_sel_hi:[1,0]
	v_pk_mul_f32 v[148:149], v[118:119], v[132:133] op_sel_hi:[1,0]
	v_pk_mul_f32 v[154:155], v[124:125], v[132:133] op_sel_hi:[1,0]
	v_pk_mul_f32 v[152:153], v[122:123], v[132:133] op_sel_hi:[1,0]
	v_mov_b32_e32 v132, v130
	v_mov_b32_e32 v133, v130
	v_mov_b64_e32 v[138:139], v[132:133]
	v_sub_f32_e32 v159, v159, v5
	v_sub_f32_e32 v158, v158, v5
	v_sub_f32_e32 v157, v157, v5
	v_sub_f32_e32 v156, v156, v5
	v_sub_f32_e32 v163, v163, v5
	v_sub_f32_e32 v162, v162, v5
	v_sub_f32_e32 v161, v161, v5
	v_sub_f32_e32 v160, v160, v5
	v_mov_b64_e32 v[136:137], v[130:131]
	s_branch .LBB0_1389

.LBB0_1392:
	s_nop 0
	v_mfma_f32_16x16x32_bf16 v[110:113], v[30:33], v[132:135], v[140:143]
	s_add_i32 s0, s30, -2
	s_mov_b64 s[12:13], -1
	s_cmp_ge_u32 s0, s59
	s_nop 0
	v_mfma_f32_16x16x32_bf16 v[114:117], v[34:37], v[132:135], v[144:147]
	s_nop 0
	v_mfma_f32_16x16x32_bf16 v[118:121], v[38:41], v[132:135], v[148:151]
	s_nop 0
	v_mfma_f32_16x16x32_bf16 v[122:125], v[42:45], v[132:135], v[152:155]
	s_cbranch_scc1 .LBB0_1378
	s_add_i32 s62, s30, 1
	s_cmp_gt_u32 s62, s59
	s_cbranch_scc1 .LBB0_1395
	v_add_co_u32_e32 v26, vcc, 0xffffb000, v196
	s_nop 1
	v_addc_co_u32_e32 v27, vcc, -1, v197, vcc
	v_add_co_u32_e32 v42, vcc, 0xffffc000, v196
	global_load_dwordx4 v[14:17], v[26:27], off offset:-3072
	global_load_dwordx4 v[18:21], v[26:27], off offset:-2048
	global_load_dwordx4 v[22:25], v[26:27], off offset:-1024
	s_nop 0
	global_load_dwordx4 v[26:29], v[26:27], off
	v_addc_co_u32_e32 v43, vcc, -1, v197, vcc
	global_load_dwordx4 v[30:33], v[42:43], off offset:-3072
	global_load_dwordx4 v[34:37], v[42:43], off offset:-2048
	global_load_dwordx4 v[38:41], v[42:43], off offset:-1024
	s_nop 0
	global_load_dwordx4 v[42:45], v[42:43], off
	s_waitcnt vmcnt(16)
	s_branch .Lp6w_1
.LBB0_1395:
	s_waitcnt vmcnt(0)
.Lp6w_1:
	s_add_i32 s0, s61, 32
	s_cmp_ge_u32 s0, s60
	s_cselect_b64 s[12:13], -1, 0
	s_add_i32 s0, s61, 63
	s_cmp_le_u32 s0, s56
	s_cselect_b64 s[14:15], -1, 0
	s_and_b64 s[14:15], s[12:13], s[14:15]
	s_mov_b64 s[12:13], -1
	s_and_b64 vcc, exec, s[14:15]
	s_cbranch_vccnz .LBB0_1399
	v_add_u32_e32 v4, s61, v164
	v_add_u32_e32 v126, 32, v4
	v_cmp_ge_i32_e32 vcc, v126, v238
	v_cmp_le_u32_e64 s[12:13], v126, v195
	v_add_u32_e32 v126, 33, v4
	s_and_b64 s[16:17], s[12:13], vcc
	v_cmp_lt_i32_e32 vcc, v126, v238
	v_cmp_gt_u32_e64 s[12:13], v126, v195
	v_add_u32_e32 v126, 34, v4
	s_or_b64 s[14:15], s[12:13], vcc
	v_cmp_lt_i32_e32 vcc, v126, v238
	v_cmp_gt_u32_e64 s[12:13], v126, v195
	v_add_u32_e32 v126, 35, v4
	s_or_b64 s[12:13], s[12:13], vcc
	v_cmp_lt_i32_e32 vcc, v126, v238
	v_cmp_gt_u32_e64 s[18:19], v126, v195
	v_add_u32_e32 v126, 48, v4
	s_or_b64 vcc, s[18:19], vcc
	v_cmp_lt_i32_e64 s[18:19], v126, v238
	v_cmp_gt_u32_e64 s[20:21], v126, v195
	v_add_u32_e32 v126, 49, v4
	s_or_b64 s[24:25], s[20:21], s[18:19]
	v_cmp_lt_i32_e64 s[18:19], v126, v238
	v_cmp_gt_u32_e64 s[20:21], v126, v195
	v_add_u32_e32 v126, 50, v4
	s_or_b64 s[22:23], s[20:21], s[18:19]
	v_cmp_lt_i32_e64 s[18:19], v126, v238
	v_cmp_gt_u32_e64 s[20:21], v126, v195
	v_mfma_f32_16x16x32_bf16 v[126:129], v[50:53], v[6:9], 0
	v_add_u32_e32 v4, 51, v4
	s_or_b64 s[20:21], s[20:21], s[18:19]
	v_cmp_lt_i32_e64 s[18:19], v4, v238
	v_mfma_f32_16x16x32_bf16 v[132:135], v[46:49], v[6:9], 0
	v_cmp_gt_u32_e64 s[26:27], v4, v195
	s_or_b64 s[18:19], s[26:27], s[18:19]
	v_mov_b64_e32 v[154:155], v[124:125]
	v_mfma_f32_16x16x32_bf16 v[126:129], v[54:57], v[10:13], v[126:129]
	v_mov_b64_e32 v[150:151], v[120:121]
	v_mov_b64_e32 v[146:147], v[116:117]
	v_mov_b64_e32 v[152:153], v[122:123]
	v_mfma_f32_16x16x32_bf16 v[140:143], v[62:65], v[10:13], v[132:135]
	v_mov_b64_e32 v[148:149], v[118:119]
	s_nop 2
	v_cndmask_b32_e64 v157, v229, v126, s[16:17]
	v_cndmask_b32_e64 v159, v127, v229, s[14:15]
	v_cndmask_b32_e64 v160, v128, v229, s[12:13]
	v_cndmask_b32_e32 v161, v129, v229, vcc
	v_max_f32_e32 v4, v159, v159
	v_max_f32_e32 v126, v157, v157
	v_cndmask_b32_e64 v156, v142, v229, s[20:21]
	v_cndmask_b32_e64 v158, v143, v229, s[18:19]
	v_max_f32_e32 v4, v126, v4
	v_max_f32_e32 v126, v161, v161
	v_max_f32_e32 v127, v160, v160
	v_max_f32_e32 v126, v127, v126
	v_max_f32_e32 v127, v158, v158
	v_max_f32_e32 v128, v156, v156
	v_cndmask_b32_e64 v134, v140, v229, s[24:25]
	v_cndmask_b32_e64 v135, v141, v229, s[22:23]
	v_max_f32_e32 v127, v128, v127
	v_max3_f32 v127, v134, v135, v127
	v_max3_f32 v163, v4, v126, v127
	v_add_f32_e32 v4, 0x41380000, v2
	v_cmp_le_f32_e32 vcc, v163, v4
	v_mov_b64_e32 v[142:143], v[138:139]
	v_mov_b64_e32 v[128:129], v[112:113]
	s_cmp_lg_u64 vcc, exec
	v_mov_b64_e32 v[140:141], v[136:137]
	v_mov_b32_e32 v4, v2
	v_mov_b64_e32 v[144:145], v[114:115]
	v_mov_b64_e32 v[126:127], v[110:111]
	v_mov_b32_e32 v162, v5
	v_mov_b32_e32 v132, v130
	v_mov_b32_e32 v133, v131
	v_mov_b32_e32 v243, v241
	v_mov_b32_e32 v244, v242
	s_cbranch_scc0 .LBB0_1398
	v_mov_b32_e32 v4, v163
	s_nop 1
	v_permlane16_swap_b32_e32 v163, v4
	v_max_f32_e32 v4, v4, v4
	v_max_f32_e32 v126, v163, v163
	v_max_f32_e32 v4, v126, v4
	v_mov_b32_e32 v126, v4
	s_nop 1
	v_permlane32_swap_b32_e32 v4, v126
	v_max3_f32 v4, v2, v4, v126
	v_cmp_neq_f32_e32 vcc, s76, v4
	s_nop 1
	v_cndmask_b32_e32 v126, 0, v4, vcc
	v_sub_f32_e32 v127, v2, v126
	v_exp_f32_e32 v132, v127
	v_xor_b32_e32 v140, 0x80000000, v126
	v_mov_b32_e32 v141, v140
	v_mov_b32_e32 v142, v140
	v_mul_f32_e32 v162, v5, v132
	v_pk_mul_f32 v[128:129], v[112:113], v[132:133] op_sel_hi:[1,0]
	v_pk_mul_f32 v[126:127], v[110:111], v[132:133] op_sel_hi:[1,0]
	v_pk_mul_f32 v[146:147], v[116:117], v[132:133] op_sel_hi:[1,0]
	v_pk_mul_f32 v[144:145], v[114:115], v[132:133] op_sel_hi:[1,0]
	v_pk_mul_f32 v[150:151], v[120:121], v[132:133] op_sel_hi:[1,0]
	v_pk_mul_f32 v[148:149], v[118:119], v[132:133] op_sel_hi:[1,0]
	v_pk_mul_f32 v[154:155], v[124:125], v[132:133] op_sel_hi:[1,0]
	v_pk_mul_f32 v[152:153], v[122:123], v[132:133] op_sel_hi:[1,0]
	v_mov_b32_e32 v143, v140
	v_mov_b32_e32 v132, v140
	v_mov_b32_e32 v133, v140
	v_mov_b32_e32 v243, v140
	v_mov_b32_e32 v244, v140

.LBB0_1406:
	s_nop 0
	v_mfma_f32_16x16x32_bf16 v[110:113], v[58:61], v[156:159], v[126:129]
	s_mov_b64 s[12:13], -1
	s_andn2_b64 vcc, exec, s[44:45]
	v_mfma_f32_16x16x32_bf16 v[114:117], v[66:69], v[156:159], v[144:147]
	v_mfma_f32_16x16x32_bf16 v[118:121], v[70:73], v[156:159], v[148:151]
	v_mfma_f32_16x16x32_bf16 v[122:125], v[74:77], v[156:159], v[152:155]
	s_cbranch_vccnz .LBB0_1416
	s_add_i32 s0, s30, 2
	s_cmp_gt_u32 s0, s59
	s_cbranch_scc1 .LBB0_1409
	v_add_co_u32_e32 v50, vcc, 0xfffff000, v196
	s_nop 1
	v_addc_co_u32_e32 v51, vcc, -1, v197, vcc
	global_load_dwordx4 v[46:49], v[50:51], off offset:-2048
	global_load_dwordx4 v[54:57], v[50:51], off offset:-1024
	global_load_dwordx4 v[62:65], v[196:197], off offset:-4096
	global_load_dwordx4 v[58:61], v[196:197], off offset:-3072
	global_load_dwordx4 v[66:69], v[196:197], off offset:-2048
	global_load_dwordx4 v[70:73], v[196:197], off offset:-1024
	s_nop 0
	global_load_dwordx4 v[50:53], v[50:51], off offset:-3072
	s_nop 0
	global_load_dwordx4 v[74:77], v[196:197], off
	s_waitcnt vmcnt(16)
	s_branch .Lp6w_2
.LBB0_1409:
	s_waitcnt vmcnt(0)
.Lp6w_2:
	s_add_i32 s0, s61, 64
	s_cmp_ge_u32 s0, s60
	s_cselect_b64 s[12:13], -1, 0
	s_add_i32 s0, s61, 0x5f
	s_cmp_le_u32 s0, s56
	s_cselect_b64 s[14:15], -1, 0
	s_and_b64 s[14:15], s[12:13], s[14:15]
	s_mov_b64 s[12:13], -1
	s_and_b64 vcc, exec, s[14:15]
	s_cbranch_vccnz .LBB0_1413
	v_add_u32_e32 v2, s61, v164
	v_add_u32_e32 v5, 64, v2
	v_add_u32_e32 v126, 0x23f, v2
	v_cmp_ge_u32_e32 vcc, v126, v195
	v_cmp_le_u32_e64 s[12:13], v5, v195
	v_add_u32_e32 v126, 0x240, v2
	s_and_b64 s[16:17], s[12:13], vcc
	v_cmp_lt_u32_e32 vcc, v126, v195
	v_cmp_ge_u32_e64 s[12:13], v5, v195
	v_add_u32_e32 v5, 0x42, v2
	v_add_u32_e32 v126, 0x241, v2
	s_or_b64 vcc, s[12:13], vcc
	v_cmp_lt_u32_e64 s[12:13], v126, v195
	v_cmp_gt_u32_e64 s[14:15], v5, v195
	v_add_u32_e32 v5, 0x43, v2
	v_add_u32_e32 v126, 0x242, v2
	s_or_b64 s[12:13], s[14:15], s[12:13]
	v_cmp_lt_u32_e64 s[14:15], v126, v195
	v_cmp_gt_u32_e64 s[18:19], v5, v195
	v_add_u32_e32 v5, 0x50, v2
	v_add_u32_e32 v126, 0x24f, v2
	s_or_b64 s[14:15], s[18:19], s[14:15]
	v_cmp_lt_u32_e64 s[18:19], v126, v195
	v_cmp_gt_u32_e64 s[20:21], v5, v195
	v_add_u32_e32 v5, 0x51, v2
	v_add_u32_e32 v126, 0x250, v2
	s_or_b64 s[22:23], s[20:21], s[18:19]
	v_cmp_lt_u32_e64 s[18:19], v126, v195
	v_cmp_gt_u32_e64 s[20:21], v5, v195
	v_add_u32_e32 v126, 0x251, v2
	s_or_b64 s[24:25], s[20:21], s[18:19]
	v_cmp_lt_u32_e64 s[18:19], v126, v195
	v_mfma_f32_16x16x32_bf16 v[126:129], v[90:93], v[6:9], 0
	v_add_u32_e32 v5, 0x52, v2
	v_cmp_gt_u32_e64 s[20:21], v5, v195
	v_add_u32_e32 v5, 0x53, v2
	v_mfma_f32_16x16x32_bf16 v[134:137], v[86:89], v[6:9], 0
	v_add_u32_e32 v2, 0x252, v2
	s_or_b64 s[20:21], s[20:21], s[18:19]
	v_cmp_lt_u32_e64 s[18:19], v2, v195
	v_mfma_f32_16x16x32_bf16 v[126:129], v[82:85], v[10:13], v[126:129]
	v_cmp_gt_u32_e64 s[26:27], v5, v195
	s_or_b64 s[18:19], s[26:27], s[18:19]
	v_mov_b64_e32 v[154:155], v[124:125]
	v_mfma_f32_16x16x32_bf16 v[134:137], v[78:81], v[10:13], v[134:137]
	v_mov_b64_e32 v[150:151], v[120:121]
	s_nop 2
	v_cndmask_b32_e64 v131, v229, v126, s[16:17]
	v_cndmask_b32_e32 v139, v127, v229, vcc
	v_cndmask_b32_e64 v156, v128, v229, s[12:13]
	v_cndmask_b32_e64 v157, v129, v229, s[14:15]
	v_max_f32_e32 v126, v139, v139
	v_max_f32_e32 v127, v131, v131
	v_cndmask_b32_e64 v130, v136, v229, s[20:21]
	v_cndmask_b32_e64 v138, v137, v229, s[18:19]
	v_max_f32_e32 v126, v127, v126
	v_max_f32_e32 v127, v157, v157
	v_max_f32_e32 v128, v156, v156
	v_max_f32_e32 v127, v128, v127
	v_max_f32_e32 v128, v138, v138
	v_max_f32_e32 v129, v130, v130
	v_cndmask_b32_e64 v2, v134, v229, s[22:23]
	v_cndmask_b32_e64 v5, v135, v229, s[24:25]
	v_max_f32_e32 v128, v129, v128
	v_max3_f32 v128, v2, v5, v128
	v_max3_f32 v159, v126, v127, v128
	v_add_f32_e32 v126, 0x41380000, v4
	v_cmp_le_f32_e32 vcc, v159, v126
	v_mov_b64_e32 v[146:147], v[116:117]
	v_mov_b64_e32 v[136:137], v[112:113]
	s_cmp_lg_u64 vcc, exec
	v_mov_b32_e32 v239, v4
	v_mov_b64_e32 v[152:153], v[122:123]
	v_mov_b64_e32 v[148:149], v[118:119]
	v_mov_b64_e32 v[144:145], v[114:115]
	v_mov_b64_e32 v[134:135], v[110:111]
	v_mov_b32_e32 v158, v160
	v_mov_b32_e32 v126, v132
	v_mov_b32_e32 v127, v133
	v_mov_b32_e32 v128, v243
	v_mov_b32_e32 v129, v244
	s_cbranch_scc0 .LBB0_1412
	v_mov_b32_e32 v126, v159
	s_nop 1
	v_permlane16_swap_b32_e32 v159, v126
	v_max_f32_e32 v126, v126, v126
	v_max_f32_e32 v127, v159, v159
	v_max_f32_e32 v126, v127, v126
	v_mov_b32_e32 v127, v126
	s_nop 1
	v_permlane32_swap_b32_e32 v126, v127
	v_max3_f32 v239, v4, v126, v127
	v_cmp_neq_f32_e32 vcc, s76, v239
	s_nop 1
	v_cndmask_b32_e32 v126, 0, v239, vcc
	v_sub_f32_e32 v127, v4, v126
	v_exp_f32_e32 v128, v127
	v_xor_b32_e32 v126, 0x80000000, v126
	v_mov_b32_e32 v127, v126
	v_mul_f32_e32 v158, v160, v128
	v_pk_mul_f32 v[136:137], v[112:113], v[128:129] op_sel_hi:[1,0]
	v_pk_mul_f32 v[134:135], v[110:111], v[128:129] op_sel_hi:[1,0]
	v_pk_mul_f32 v[146:147], v[116:117], v[128:129] op_sel_hi:[1,0]
	v_pk_mul_f32 v[144:145], v[114:115], v[128:129] op_sel_hi:[1,0]
	v_pk_mul_f32 v[150:151], v[120:121], v[128:129] op_sel_hi:[1,0]
	v_pk_mul_f32 v[148:149], v[118:119], v[128:129] op_sel_hi:[1,0]
	v_pk_mul_f32 v[154:155], v[124:125], v[128:129] op_sel_hi:[1,0]
	v_pk_mul_f32 v[152:153], v[122:123], v[128:129] op_sel_hi:[1,0]
	v_mov_b32_e32 v128, v126
	v_mov_b32_e32 v129, v126

.LBB0_1434:
	s_cmp_eq_u64 s[20:21], 0
	s_mov_b64 s[22:23], 0
	s_cbranch_scc1 .LBB0_1436
	s_ff1_i32_b64 s0, s[20:21]
	v_readlane_b32 s18, v238, s0
	s_add_u32 s22, s20, -1
	s_addc_u32 s23, s21, -1
	s_ashr_i32 s19, s18, 31
	s_and_b64 s[22:23], s[22:23], s[20:21]
	s_lshl_b64 s[20:21], s[18:19], 14
	s_add_u32 s20, s57, s20
	s_addc_u32 s21, s58, s21
	s_add_u32 s24, s20, 0x1000
	s_addc_u32 s25, s21, 0
	global_load_dwordx4 v[122:125], v234, s[20:21]
	global_load_dwordx4 v[118:121], v234, s[20:21] offset:1024
	global_load_dwordx4 v[114:117], v234, s[20:21] offset:2048
	global_load_dwordx4 v[110:113], v234, s[20:21] offset:3072
	global_load_dwordx4 v[106:109], v234, s[24:25]
	global_load_dwordx4 v[102:105], v235, s[24:25]
	global_load_dwordx4 v[98:101], v236, s[24:25]
	global_load_dwordx4 v[94:97], v237, s[24:25]
	s_waitcnt vmcnt(16)
	s_branch .Lp6w_3

.Lp6w_3:
	s_lshl_b32 s15, s14, 5
	s_or_b32 s0, s15, 31
	s_cmp_le_i32 s0, s30
	s_mov_b64 s[20:21], -1
	s_cbranch_scc0 .LBB0_1443
	s_nop 0
	v_mfma_f32_16x16x32_bf16 v[130:133], v[14:17], v[6:9], v[126:129]
	v_cmp_eq_f32_e32 vcc, s76, v240
	s_nop 0
	v_mfma_f32_16x16x32_bf16 v[160:163], v[22:25], v[10:13], v[130:133]
	v_mfma_f32_16x16x32_bf16 v[130:133], v[18:21], v[6:9], v[126:129]
	s_nop 0
	v_mfma_f32_16x16x32_bf16 v[156:159], v[26:29], v[10:13], v[130:133]
	s_nop 4
	v_max_f32_e32 v2, v161, v161
	v_max_f32_e32 v4, v160, v160
	v_max_f32_e32 v2, v4, v2
	v_max_f32_e32 v4, v163, v163
	v_max_f32_e32 v5, v162, v162
	v_max_f32_e32 v4, v5, v4
	v_max_f32_e32 v5, v159, v159
	v_max_f32_e32 v130, v158, v158
	v_max_f32_e32 v5, v130, v5
	v_max3_f32 v5, v156, v157, v5
	v_max3_f32 v2, v2, v4, v5
	v_cndmask_b32_e32 v4, v230, v229, vcc
	v_cmp_le_f32_e32 vcc, v2, v4
	s_cmp_lg_u64 vcc, exec
	s_cbranch_scc0 .LBB0_1439
	v_sub_f32_e32 v2, v2, v126
	v_mov_b32_e32 v4, v2
	s_nop 1
	v_permlane16_swap_b32_e32 v2, v4
	v_max_f32_e32 v4, v4, v4
	v_max_f32_e32 v2, v2, v2
	v_max_f32_e32 v2, v2, v4
	v_mov_b32_e32 v4, v2
	s_nop 1
	v_permlane32_swap_b32_e32 v2, v4
	v_max3_f32 v2, v240, v2, v4
	v_cmp_neq_f32_e32 vcc, s76, v2
	s_mov_b64 s[20:21], 0
	s_nop 0
	v_cndmask_b32_e32 v5, 0, v2, vcc
	v_sub_f32_e32 v4, v240, v5
	v_exp_f32_e32 v132, v4
	v_xor_b32_e32 v130, 0x80000000, v5
	v_add_f32_e32 v5, v126, v5
	v_mov_b32_e32 v131, v130
	v_mul_f32_e32 v4, v241, v132
	v_pk_mul_f32 v[142:143], v[68:69], v[132:133] op_sel_hi:[1,0]
	v_pk_mul_f32 v[140:141], v[66:67], v[132:133] op_sel_hi:[1,0]
	v_pk_mul_f32 v[146:147], v[56:57], v[132:133] op_sel_hi:[1,0]
	v_pk_mul_f32 v[144:145], v[54:55], v[132:133] op_sel_hi:[1,0]
	v_pk_mul_f32 v[150:151], v[52:53], v[132:133] op_sel_hi:[1,0]
	v_pk_mul_f32 v[148:149], v[50:51], v[132:133] op_sel_hi:[1,0]
	v_pk_mul_f32 v[154:155], v[48:49], v[132:133] op_sel_hi:[1,0]
	v_pk_mul_f32 v[152:153], v[46:47], v[132:133] op_sel_hi:[1,0]
	v_mov_b32_e32 v132, v130
	v_mov_b32_e32 v133, v130
	v_mov_b64_e32 v[138:139], v[132:133]
	v_sub_f32_e32 v159, v159, v5
	v_sub_f32_e32 v158, v158, v5
	v_sub_f32_e32 v157, v157, v5
	v_sub_f32_e32 v156, v156, v5
	v_sub_f32_e32 v163, v163, v5
	v_sub_f32_e32 v162, v162, v5
	v_sub_f32_e32 v161, v161, v5
	v_sub_f32_e32 v160, v160, v5
	v_mov_b64_e32 v[136:137], v[130:131]
	s_branch .LBB0_1440

.LBB0_1443:
	s_and_b64 vcc, exec, s[20:21]
	s_cbranch_vccz .LBB0_1448
	s_nop 0
	v_mfma_f32_16x16x32_bf16 v[130:133], v[14:17], v[6:9], 0
	v_or_b32_e32 v4, s15, v177
	s_or_b32 s0, s15, 4
	v_cmp_ge_i32_e32 vcc, s30, v4
	s_nop 0
	v_mfma_f32_16x16x32_bf16 v[134:137], v[18:21], v[6:9], 0
	s_or_b32 s1, s15, 5
	v_or_b32_e32 v5, s15, v198
	s_or_b32 s17, s15, 6
	s_nop 0
	v_mfma_f32_16x16x32_bf16 v[138:141], v[22:25], v[10:13], v[130:133]
	v_or_b32_e32 v142, s15, v199
	s_or_b32 s15, s15, 7
	s_nop 0
	v_mfma_f32_16x16x32_bf16 v[134:137], v[26:29], v[10:13], v[134:137]
	s_nop 3
	v_cndmask_b32_e32 v133, v229, v138, vcc
	v_cmp_le_i32_e32 vcc, s0, v239
	v_max_f32_e32 v130, v133, v133
	s_nop 0
	v_cndmask_b32_e32 v2, v229, v134, vcc
	v_cmp_gt_i32_e32 vcc, s30, v4
	s_nop 1
	v_cndmask_b32_e32 v134, v229, v139, vcc
	v_cmp_le_i32_e32 vcc, s1, v239
	s_nop 1
	v_cndmask_b32_e32 v4, v229, v135, vcc
	v_cmp_ge_i32_e32 vcc, s30, v5
	v_max_f32_e32 v5, v134, v134
	v_max_f32_e32 v5, v130, v5
	v_cndmask_b32_e32 v135, v229, v140, vcc
	v_cmp_le_i32_e32 vcc, s17, v239
	s_nop 1
	v_cndmask_b32_e32 v131, v229, v136, vcc
	v_cmp_ge_i32_e32 vcc, s30, v142
	v_max_f32_e32 v138, v131, v131
	s_nop 0
	v_cndmask_b32_e32 v136, v229, v141, vcc
	v_cmp_le_i32_e32 vcc, s15, v239
	v_max_f32_e32 v130, v136, v136
	s_nop 0
	v_cndmask_b32_e32 v132, v229, v137, vcc
	v_max_f32_e32 v137, v135, v135
	v_max_f32_e32 v130, v137, v130
	v_max_f32_e32 v137, v132, v132
	v_max_f32_e32 v137, v138, v137
	v_max3_f32 v137, v2, v4, v137
	v_max3_f32 v5, v5, v130, v137
	v_add_f32_e32 v130, 0x41380000, v240
	v_cmp_le_f32_e32 vcc, v5, v130
	s_cmp_lg_u64 vcc, exec
	s_cbranch_scc0 .LBB0_1446
	v_mov_b32_e32 v126, v5
	s_nop 1
	v_permlane16_swap_b32_e32 v5, v126
	v_max_f32_e32 v126, v126, v126
	v_max_f32_e32 v5, v5, v5
	v_max_f32_e32 v5, v5, v126
	v_mov_b32_e32 v126, v5
	s_nop 1
	v_permlane32_swap_b32_e32 v5, v126
	v_max3_f32 v5, v240, v5, v126
	v_cmp_neq_f32_e32 vcc, s76, v5
	s_nop 1
	v_cndmask_b32_e32 v126, 0, v5, vcc
	v_sub_f32_e32 v127, v240, v126
	v_exp_f32_e32 v128, v127
	v_xor_b32_e32 v126, 0x80000000, v126
	v_mov_b32_e32 v127, v126
	v_mov_b32_e32 v240, v5
	v_mul_f32_e32 v241, v241, v128
	v_pk_mul_f32 v[68:69], v[68:69], v[128:129] op_sel_hi:[1,0]
	v_pk_mul_f32 v[66:67], v[66:67], v[128:129] op_sel_hi:[1,0]
	v_pk_mul_f32 v[56:57], v[56:57], v[128:129] op_sel_hi:[1,0]
	v_pk_mul_f32 v[54:55], v[54:55], v[128:129] op_sel_hi:[1,0]
	v_pk_mul_f32 v[52:53], v[52:53], v[128:129] op_sel_hi:[1,0]
	v_pk_mul_f32 v[50:51], v[50:51], v[128:129] op_sel_hi:[1,0]
	v_pk_mul_f32 v[48:49], v[48:49], v[128:129] op_sel_hi:[1,0]
	v_pk_mul_f32 v[46:47], v[46:47], v[128:129] op_sel_hi:[1,0]
	v_mov_b32_e32 v128, v126
	v_mov_b32_e32 v129, v126
	v_mov_b32_e32 v130, v126
	v_mov_b32_e32 v5, v126
	v_mov_b32_e32 v242, v126
	v_mov_b32_e32 v243, v126
	s_branch .LBB0_1447

.LBB0_1448:
	s_nop 0
	v_mfma_f32_16x16x32_bf16 v[66:69], v[30:33], v[132:135], v[140:143]
	s_mov_b64 s[26:27], -1
	s_cmp_eq_u32 s45, 1
	s_nop 0
	v_mfma_f32_16x16x32_bf16 v[54:57], v[34:37], v[132:135], v[144:147]
	s_nop 0
	v_mfma_f32_16x16x32_bf16 v[50:53], v[38:41], v[132:135], v[148:151]
	s_nop 0
	v_mfma_f32_16x16x32_bf16 v[46:49], v[42:45], v[132:135], v[152:155]
	s_cbranch_scc1 .LBB0_1433
	s_cmp_eq_u64 s[22:23], 0
	s_mov_b64 s[24:25], 0
	s_cbranch_scc1 .LBB0_1451
	s_ff1_i32_b64 s0, s[22:23]
	v_readlane_b32 s14, v238, s0
	s_add_u32 s20, s22, -1
	s_addc_u32 s21, s23, -1
	s_ashr_i32 s15, s14, 31
	s_and_b64 s[24:25], s[20:21], s[22:23]
	s_lshl_b64 s[20:21], s[14:15], 14
	s_add_u32 s20, s57, s20
	s_addc_u32 s21, s58, s21
	s_add_u32 s22, s20, 0x1000
	s_addc_u32 s23, s21, 0
	global_load_dwordx4 v[14:17], v234, s[20:21]
	global_load_dwordx4 v[18:21], v234, s[20:21] offset:1024
	global_load_dwordx4 v[22:25], v234, s[20:21] offset:2048
	global_load_dwordx4 v[26:29], v234, s[20:21] offset:3072
	global_load_dwordx4 v[30:33], v234, s[22:23]
	global_load_dwordx4 v[34:37], v235, s[22:23]
	global_load_dwordx4 v[38:41], v236, s[22:23]
	global_load_dwordx4 v[42:45], v237, s[22:23]
	s_waitcnt vmcnt(16)
	s_branch .Lp6w_4
.LBB0_1451:
	s_waitcnt vmcnt(0)
.Lp6w_4:
	s_lshl_b32 s15, s16, 5
	s_or_b32 s0, s15, 31
	s_cmp_le_i32 s0, s30
	s_mov_b64 s[20:21], -1
	s_cbranch_scc0 .LBB0_1458
	v_mfma_f32_16x16x32_bf16 v[126:129], v[58:61], v[6:9], v[136:139]
	v_cmp_eq_f32_e32 vcc, s76, v2
	v_mfma_f32_16x16x32_bf16 v[160:163], v[70:73], v[10:13], v[126:129]
	s_nop 7
	v_max_f32_e32 v4, v161, v161
	v_max_f32_e32 v126, v160, v160
	v_max_f32_e32 v4, v126, v4
	v_mfma_f32_16x16x32_bf16 v[126:129], v[62:65], v[6:9], v[136:139]
	v_max_f32_e32 v132, v163, v163
	v_max_f32_e32 v133, v162, v162
	v_max_f32_e32 v132, v133, v132
	v_mfma_f32_16x16x32_bf16 v[156:159], v[74:77], v[10:13], v[126:129]
	s_nop 7
	v_max_f32_e32 v126, v159, v159
	v_max_f32_e32 v127, v158, v158
	v_max_f32_e32 v126, v127, v126
	v_max3_f32 v126, v156, v157, v126
	v_max3_f32 v4, v4, v132, v126
	v_cndmask_b32_e32 v126, v230, v229, vcc
	v_cmp_le_f32_e32 vcc, v4, v126
	s_cmp_lg_u64 vcc, exec
	s_cbranch_scc0 .LBB0_1454
	v_sub_f32_e32 v4, v4, v130
	v_mov_b32_e32 v126, v4
	s_nop 1
	v_permlane16_swap_b32_e32 v4, v126
	v_max_f32_e32 v126, v126, v126
	v_max_f32_e32 v4, v4, v4
	v_max_f32_e32 v4, v4, v126
	v_mov_b32_e32 v126, v4
	s_nop 1
	v_permlane32_swap_b32_e32 v4, v126
	v_max3_f32 v4, v2, v4, v126
	v_cmp_neq_f32_e32 vcc, s76, v4
	s_mov_b64 s[20:21], 0
	s_nop 0
	v_cndmask_b32_e32 v133, 0, v4, vcc
	v_sub_f32_e32 v126, v2, v133
	v_exp_f32_e32 v134, v126
	v_xor_b32_e32 v132, 0x80000000, v133
	v_add_f32_e32 v133, v130, v133
	v_sub_f32_e32 v159, v159, v133
	v_mul_f32_e32 v240, v131, v134
	v_pk_mul_f32 v[128:129], v[68:69], v[134:135] op_sel_hi:[1,0]
	v_pk_mul_f32 v[126:127], v[66:67], v[134:135] op_sel_hi:[1,0]
	v_pk_mul_f32 v[146:147], v[56:57], v[134:135] op_sel_hi:[1,0]
	v_pk_mul_f32 v[144:145], v[54:55], v[134:135] op_sel_hi:[1,0]
	v_pk_mul_f32 v[150:151], v[52:53], v[134:135] op_sel_hi:[1,0]
	v_pk_mul_f32 v[148:149], v[50:51], v[134:135] op_sel_hi:[1,0]
	v_pk_mul_f32 v[154:155], v[48:49], v[134:135] op_sel_hi:[1,0]
	v_pk_mul_f32 v[152:153], v[46:47], v[134:135] op_sel_hi:[1,0]
	v_mov_b32_e32 v134, v132
	v_mov_b32_e32 v135, v132
	v_sub_f32_e32 v158, v158, v133
	v_sub_f32_e32 v157, v157, v133
	v_sub_f32_e32 v156, v156, v133
	v_sub_f32_e32 v163, v163, v133
	v_sub_f32_e32 v162, v162, v133
	v_sub_f32_e32 v161, v161, v133
	v_sub_f32_e32 v160, v160, v133
	v_mov_b32_e32 v133, v132
	v_mov_b64_e32 v[142:143], v[134:135]
	v_mov_b64_e32 v[140:141], v[132:133]
	s_branch .LBB0_1455

.LBB0_1462:
	v_mfma_f32_16x16x32_bf16 v[66:69], v[78:81], v[156:159], v[126:129]
	s_cmp_eq_u32 s45, 2
	v_mfma_f32_16x16x32_bf16 v[54:57], v[82:85], v[156:159], v[144:147]
	v_mfma_f32_16x16x32_bf16 v[50:53], v[86:89], v[156:159], v[148:151]
	v_mfma_f32_16x16x32_bf16 v[46:49], v[90:93], v[156:159], v[152:155]
	s_cbranch_scc1 .LBB0_1468
	s_cmp_eq_u64 s[24:25], 0
	s_mov_b64 s[20:21], 0
	s_cbranch_scc1 .LBB0_1465
	s_ff1_i32_b64 s0, s[24:25]
	v_readlane_b32 s16, v238, s0
	s_add_u32 s20, s24, -1
	s_addc_u32 s21, s25, -1
	s_ashr_i32 s17, s16, 31
	s_and_b64 s[20:21], s[20:21], s[24:25]
	s_lshl_b64 s[22:23], s[16:17], 14
	s_add_u32 s22, s57, s22
	s_addc_u32 s23, s58, s23
	s_add_u32 s24, s22, 0x1000
	s_addc_u32 s25, s23, 0
	global_load_dwordx4 v[58:61], v234, s[22:23]
	global_load_dwordx4 v[62:65], v234, s[22:23] offset:1024
	global_load_dwordx4 v[70:73], v234, s[22:23] offset:2048
	global_load_dwordx4 v[74:77], v234, s[22:23] offset:3072
	global_load_dwordx4 v[78:81], v234, s[24:25]
	global_load_dwordx4 v[82:85], v235, s[24:25]
	global_load_dwordx4 v[86:89], v236, s[24:25]
	global_load_dwordx4 v[90:93], v237, s[24:25]
	s_waitcnt vmcnt(16)
	s_branch .Lp6w_5
.LBB0_1465:
	s_waitcnt vmcnt(0)
.Lp6w_5:
	s_lshl_b32 s15, s18, 5
	s_or_b32 s0, s15, 31
	s_cmp_le_i32 s0, s30
	s_mov_b64 s[22:23], -1
	s_cbranch_scc0 .LBB0_1473
	v_mfma_f32_16x16x32_bf16 v[126:129], v[122:125], v[6:9], v[140:143]
	v_cmp_eq_f32_e32 vcc, s76, v4
	v_mfma_f32_16x16x32_bf16 v[156:159], v[114:117], v[10:13], v[126:129]
	v_mfma_f32_16x16x32_bf16 v[126:129], v[118:121], v[6:9], v[140:143]
	v_mfma_f32_16x16x32_bf16 v[138:141], v[110:113], v[10:13], v[126:129]
	s_nop 5
	v_max_f32_e32 v2, v157, v157
	v_max_f32_e32 v5, v156, v156
	v_max_f32_e32 v2, v5, v2
	v_max_f32_e32 v5, v159, v159
	v_max_f32_e32 v130, v158, v158
	v_max_f32_e32 v126, v141, v141
	v_max_f32_e32 v127, v140, v140
	v_max_f32_e32 v126, v127, v126
	v_max_f32_e32 v5, v130, v5
	v_max3_f32 v126, v138, v139, v126
	v_max3_f32 v2, v2, v5, v126
	v_cndmask_b32_e32 v5, v230, v229, vcc
	v_cmp_le_f32_e32 vcc, v2, v5
	s_cmp_lg_u64 vcc, exec
	s_cbranch_scc0 .LBB0_1469
	v_sub_f32_e32 v2, v2, v132
	v_mov_b32_e32 v5, v2
	s_nop 1
	v_permlane16_swap_b32_e32 v2, v5
	v_max_f32_e32 v5, v5, v5
	v_max_f32_e32 v2, v2, v2
	v_max_f32_e32 v2, v2, v5
	v_mov_b32_e32 v5, v2
	s_nop 1
	v_permlane32_swap_b32_e32 v2, v5
	v_max3_f32 v240, v4, v2, v5
	v_cmp_neq_f32_e32 vcc, s76, v240
	s_mov_b64 s[22:23], 0
	s_nop 0
	v_cndmask_b32_e32 v5, 0, v240, vcc
	v_sub_f32_e32 v2, v4, v5
	v_exp_f32_e32 v128, v2
	v_xor_b32_e32 v126, 0x80000000, v5
	v_add_f32_e32 v5, v132, v5
	v_sub_f32_e32 v141, v141, v5
	v_mul_f32_e32 v2, v133, v128
	v_pk_mul_f32 v[136:137], v[68:69], v[128:129] op_sel_hi:[1,0]
	v_pk_mul_f32 v[134:135], v[66:67], v[128:129] op_sel_hi:[1,0]
	v_pk_mul_f32 v[146:147], v[56:57], v[128:129] op_sel_hi:[1,0]
	v_pk_mul_f32 v[144:145], v[54:55], v[128:129] op_sel_hi:[1,0]
	v_pk_mul_f32 v[150:151], v[52:53], v[128:129] op_sel_hi:[1,0]
	v_pk_mul_f32 v[148:149], v[50:51], v[128:129] op_sel_hi:[1,0]
	v_pk_mul_f32 v[154:155], v[48:49], v[128:129] op_sel_hi:[1,0]
	v_pk_mul_f32 v[152:153], v[46:47], v[128:129] op_sel_hi:[1,0]
	v_sub_f32_e32 v140, v140, v5
	v_sub_f32_e32 v139, v139, v5
	v_sub_f32_e32 v138, v138, v5
	v_sub_f32_e32 v159, v159, v5
	v_sub_f32_e32 v158, v158, v5
	v_sub_f32_e32 v157, v157, v5
	v_sub_f32_e32 v156, v156, v5
	s_branch .LBB0_1470

.LBB0_1918:
	v_readlane_b32 s0, v254, 2
	v_readlane_b32 s1, v254, 3
	s_cmp_gt_i32 s1, 6
	s_cselect_b64 s[4:5], -1, 0
	s_and_b64 s[6:7], s[28:29], s[4:5]
	s_andn2_b64 vcc, exec, s[6:7]
	s_cbranch_vccnz .LBB0_1968
	s_waitcnt vmcnt(0) lgkmcnt(0)
	s_barrier
	v_readfirstlane_b32 s0, v0
	s_lshr_b32 s0, s0, 6
	s_cmp_lg_u32 s0, 0
	s_cbranch_scc1 .Lgb5_close
	s_mov_b64 s[10:11], exec
	s_mov_b64 exec, 1
	v_readlane_b32 s12, v254, 36
	v_readlane_b32 s13, v254, 37
	v_readlane_b32 s14, v254, 38
	v_readlane_b32 s15, v254, 39
	s_nop 1
	v_mov_b32_e32 v1, s14
	ds_read_b32 v2, v1
	ds_read_b32 v3, v1 offset:4
	ds_read_b32 v4, v1 offset:8
	s_waitcnt lgkmcnt(0)
	v_readfirstlane_b32 s16, v2
	v_readfirstlane_b32 s17, v3
	v_readfirstlane_b32 s18, v4
	s_cmp_lg_u32 s16, 0
	s_cbranch_scc1 .Lgb5_have
	v_readlane_b32 s0, v254, 0
	v_readlane_b32 s1, v254, 1
	s_nop 4
	s_load_dwordx2 s[20:21], s[0:1], 0xe8
	s_load_dword s22, s[0:1], 0xf0
	v_mov_b32_e32 v5, 0
	v_mov_b32_e32 v6, 0x1000
	s_mov_b32 s19, 0
	s_waitcnt lgkmcnt(0)
	s_mul_i32 s20, s20, s21
	s_mul_i32 s20, s20, s22

.LBB0_2030:
	v_readlane_b32 s4, v254, 2
	v_readlane_b32 s5, v254, 3
	s_cmp_gt_u32 s5, 7
	s_cselect_b64 s[4:5], -1, 0
	s_and_b64 s[0:1], s[0:1], s[4:5]
	s_andn2_b64 vcc, exec, s[0:1]
	s_cbranch_vccnz .LBB0_2080
	s_waitcnt vmcnt(0) lgkmcnt(0)
	s_barrier
	v_readfirstlane_b32 s0, v0
	s_lshr_b32 s0, s0, 6
	s_cmp_lg_u32 s0, 0
	s_cbranch_scc1 .Lgb6_close
	s_mov_b64 s[10:11], exec
	s_mov_b64 exec, 1
	v_readlane_b32 s12, v254, 36
	v_readlane_b32 s13, v254, 37
	v_readlane_b32 s14, v254, 38
	v_readlane_b32 s15, v254, 39
	s_nop 1
	v_mov_b32_e32 v1, s14
	ds_read_b32 v2, v1
	ds_read_b32 v3, v1 offset:4
	ds_read_b32 v4, v1 offset:8
	s_waitcnt lgkmcnt(0)
	v_readfirstlane_b32 s16, v2
	v_readfirstlane_b32 s17, v3
	v_readfirstlane_b32 s18, v4
	s_cmp_lg_u32 s16, 0
	s_cbranch_scc1 .Lgb6_have
	v_readlane_b32 s0, v254, 0
	v_readlane_b32 s1, v254, 1
	s_nop 4
	s_load_dwordx2 s[20:21], s[0:1], 0xe8
	s_load_dword s22, s[0:1], 0xf0
	v_mov_b32_e32 v5, 0
	v_mov_b32_e32 v6, 0x1000
	s_mov_b32 s19, 0
	s_waitcnt lgkmcnt(0)
	s_mul_i32 s20, s20, s21
	s_mul_i32 s20, s20, s22

.LBB0_2170:
	v_readlane_b32 s0, v254, 2
	v_readlane_b32 s1, v254, 3
	s_cmp_gt_i32 s1, 9
	s_cselect_b64 s[4:5], -1, 0
	s_and_b64 s[0:1], s[8:9], s[4:5]
	s_andn2_b64 vcc, exec, s[0:1]
	s_cbranch_vccnz .LBB0_2220
	s_waitcnt vmcnt(0) lgkmcnt(0)
	s_barrier
	v_readfirstlane_b32 s0, v0
	s_lshr_b32 s0, s0, 6
	s_cmp_lg_u32 s0, 0
	s_cbranch_scc1 .Lgb7_close
	s_mov_b64 s[10:11], exec
	s_mov_b64 exec, 1
	v_readlane_b32 s12, v254, 36
	v_readlane_b32 s13, v254, 37
	v_readlane_b32 s14, v254, 38
	v_readlane_b32 s15, v254, 39
	s_nop 1
	v_mov_b32_e32 v1, s14
	ds_read_b32 v2, v1
	ds_read_b32 v3, v1 offset:4
	ds_read_b32 v4, v1 offset:8
	s_waitcnt lgkmcnt(0)
	v_readfirstlane_b32 s16, v2
	v_readfirstlane_b32 s17, v3
	v_readfirstlane_b32 s18, v4
	s_cmp_lg_u32 s16, 0
	s_cbranch_scc1 .Lgb7_have
	v_readlane_b32 s0, v254, 0
	v_readlane_b32 s1, v254, 1
	s_nop 4
	s_load_dwordx2 s[20:21], s[0:1], 0xe8
	s_load_dword s22, s[0:1], 0xf0
	v_mov_b32_e32 v5, 0
	v_mov_b32_e32 v6, 0x1000
	s_mov_b32 s19, 0
	s_waitcnt lgkmcnt(0)
	s_mul_i32 s20, s20, s21
	s_mul_i32 s20, s20, s22

.LBB0_2236:
	v_readlane_b32 s0, v254, 2
	v_readlane_b32 s1, v254, 3
	s_cmp_gt_i32 s1, 10
	s_cselect_b64 s[4:5], -1, 0
	s_and_b64 s[0:1], s[6:7], s[4:5]
	s_andn2_b64 vcc, exec, s[0:1]
	s_cbranch_vccnz .LBB0_2286
	s_waitcnt vmcnt(0) lgkmcnt(0)
	s_barrier
	v_readfirstlane_b32 s0, v0
	s_lshr_b32 s0, s0, 6
	s_cmp_lg_u32 s0, 0
	s_cbranch_scc1 .Lgb8_close
	s_mov_b64 s[10:11], exec
	s_mov_b64 exec, 1
	v_readlane_b32 s12, v254, 36
	v_readlane_b32 s13, v254, 37
	v_readlane_b32 s14, v254, 38
	v_readlane_b32 s15, v254, 39
	s_nop 1
	v_mov_b32_e32 v1, s14
	ds_read_b32 v2, v1
	ds_read_b32 v3, v1 offset:4
	ds_read_b32 v4, v1 offset:8
	s_waitcnt lgkmcnt(0)
	v_readfirstlane_b32 s16, v2
	v_readfirstlane_b32 s17, v3
	v_readfirstlane_b32 s18, v4
	s_cmp_lg_u32 s16, 0
	s_cbranch_scc1 .Lgb8_have
	v_readlane_b32 s0, v254, 0
	v_readlane_b32 s1, v254, 1
	s_nop 4
	s_load_dwordx2 s[20:21], s[0:1], 0xe8
	s_load_dword s22, s[0:1], 0xf0
	v_mov_b32_e32 v5, 0
	v_mov_b32_e32 v6, 0x1000
	s_mov_b32 s19, 0
	s_waitcnt lgkmcnt(0)
	s_mul_i32 s20, s20, s21
	s_mul_i32 s20, s20, s22

.LBB0_2305:
	v_readlane_b32 s0, v254, 2
	v_readlane_b32 s1, v254, 3
	s_cmp_gt_i32 s1, 11
	s_cselect_b64 s[6:7], -1, 0
	s_and_b64 s[0:1], s[4:5], s[6:7]
	s_andn2_b64 vcc, exec, s[0:1]
	s_cbranch_vccnz .LBB0_2355
	s_waitcnt vmcnt(0) lgkmcnt(0)
	s_barrier
	v_readfirstlane_b32 s0, v0
	s_lshr_b32 s0, s0, 6
	s_cmp_lg_u32 s0, 0
	s_cbranch_scc1 .Lgb9_close
	s_mov_b64 s[10:11], exec
	s_mov_b64 exec, 1
	v_readlane_b32 s12, v254, 36
	v_readlane_b32 s13, v254, 37
	v_readlane_b32 s14, v254, 38
	v_readlane_b32 s15, v254, 39
	s_nop 1
	v_mov_b32_e32 v1, s14
	ds_read_b32 v2, v1
	ds_read_b32 v3, v1 offset:4
	ds_read_b32 v4, v1 offset:8
	s_waitcnt lgkmcnt(0)
	v_readfirstlane_b32 s16, v2
	v_readfirstlane_b32 s17, v3
	v_readfirstlane_b32 s18, v4
	s_cmp_lg_u32 s16, 0
	s_cbranch_scc1 .Lgb9_have
	v_readlane_b32 s0, v254, 0
	v_readlane_b32 s1, v254, 1
	s_nop 4
	s_load_dwordx2 s[20:21], s[0:1], 0xe8
	s_load_dword s22, s[0:1], 0xf0
	v_mov_b32_e32 v5, 0
	v_mov_b32_e32 v6, 0x1000
	s_mov_b32 s19, 0
	s_waitcnt lgkmcnt(0)
	s_mul_i32 s20, s20, s21
	s_mul_i32 s20, s20, s22

.LBB0_2444:
	v_readlane_b32 s0, v254, 2
	v_readlane_b32 s1, v254, 3
	s_cmp_gt_i32 s1, 12
	s_cselect_b64 s[6:7], -1, 0
	s_and_b64 s[0:1], s[4:5], s[6:7]
	s_andn2_b64 vcc, exec, s[0:1]
	s_cbranch_vccnz .LBB0_2494
	s_waitcnt vmcnt(0) lgkmcnt(0)
	s_barrier
	v_readfirstlane_b32 s0, v0
	s_lshr_b32 s0, s0, 6
	s_cmp_lg_u32 s0, 0
	s_cbranch_scc1 .Lgb10_close
	s_mov_b64 s[10:11], exec
	s_mov_b64 exec, 1
	v_readlane_b32 s12, v254, 36
	v_readlane_b32 s13, v254, 37
	v_readlane_b32 s14, v254, 38
	v_readlane_b32 s15, v254, 39
	s_nop 1
	v_mov_b32_e32 v1, s14
	ds_read_b32 v2, v1
	ds_read_b32 v3, v1 offset:4
	ds_read_b32 v4, v1 offset:8
	s_waitcnt lgkmcnt(0)
	v_readfirstlane_b32 s16, v2
	v_readfirstlane_b32 s17, v3
	v_readfirstlane_b32 s18, v4
	s_cmp_lg_u32 s16, 0
	s_cbranch_scc1 .Lgb10_have
	v_readlane_b32 s0, v254, 0
	v_readlane_b32 s1, v254, 1
	s_nop 4
	s_load_dwordx2 s[20:21], s[0:1], 0xe8
	s_load_dword s22, s[0:1], 0xf0
	v_mov_b32_e32 v5, 0
	v_mov_b32_e32 v6, 0x1000
	s_mov_b32 s19, 0
	s_waitcnt lgkmcnt(0)
	s_mul_i32 s20, s20, s21
	s_mul_i32 s20, s20, s22

.LBB0_2568:
	v_readlane_b32 s0, v254, 2
	v_readlane_b32 s1, v254, 3
	s_cmp_gt_i32 s1, 13
	s_cselect_b64 s[4:5], -1, 0
	s_and_b64 s[0:1], s[8:9], s[4:5]
	s_andn2_b64 vcc, exec, s[0:1]
	s_cbranch_vccnz .LBB0_2618
	s_waitcnt vmcnt(0) lgkmcnt(0)
	s_barrier
	v_readfirstlane_b32 s0, v0
	s_lshr_b32 s0, s0, 6
	s_cmp_lg_u32 s0, 0
	s_cbranch_scc1 .Lgb11_close
	s_mov_b64 s[10:11], exec
	s_mov_b64 exec, 1
	v_readlane_b32 s12, v254, 36
	v_readlane_b32 s13, v254, 37
	v_readlane_b32 s14, v254, 38
	v_readlane_b32 s15, v254, 39
	s_nop 1
	v_mov_b32_e32 v1, s14
	ds_read_b32 v2, v1
	ds_read_b32 v3, v1 offset:4
	ds_read_b32 v4, v1 offset:8
	s_waitcnt lgkmcnt(0)
	v_readfirstlane_b32 s16, v2
	v_readfirstlane_b32 s17, v3
	v_readfirstlane_b32 s18, v4
	s_cmp_lg_u32 s16, 0
	s_cbranch_scc1 .Lgb11_have
	v_readlane_b32 s0, v254, 0
	v_readlane_b32 s1, v254, 1
	s_nop 4
	s_load_dwordx2 s[20:21], s[0:1], 0xe8
	s_load_dword s22, s[0:1], 0xf0
	v_mov_b32_e32 v5, 0
	v_mov_b32_e32 v6, 0x1000
	s_mov_b32 s19, 0
	s_waitcnt lgkmcnt(0)
	s_mul_i32 s20, s20, s21
	s_mul_i32 s20, s20, s22

.LBB0_2634:
	v_readlane_b32 s0, v254, 2
	v_readlane_b32 s1, v254, 3
	s_cmp_gt_i32 s1, 14
	s_cselect_b64 s[4:5], -1, 0
	s_and_b64 s[0:1], s[6:7], s[4:5]
	s_andn2_b64 vcc, exec, s[0:1]
	s_cbranch_vccnz .LBB0_2684
	s_waitcnt vmcnt(0) lgkmcnt(0)
	s_barrier
	v_readfirstlane_b32 s0, v0
	s_lshr_b32 s0, s0, 6
	s_cmp_lg_u32 s0, 0
	s_cbranch_scc1 .Lgb12_close
	s_mov_b64 s[10:11], exec
	s_mov_b64 exec, 1
	v_readlane_b32 s12, v254, 36
	v_readlane_b32 s13, v254, 37
	v_readlane_b32 s14, v254, 38
	v_readlane_b32 s15, v254, 39
	s_nop 1
	v_mov_b32_e32 v1, s14
	ds_read_b32 v2, v1
	ds_read_b32 v3, v1 offset:4
	ds_read_b32 v4, v1 offset:8
	s_waitcnt lgkmcnt(0)
	v_readfirstlane_b32 s16, v2
	v_readfirstlane_b32 s17, v3
	v_readfirstlane_b32 s18, v4
	s_cmp_lg_u32 s16, 0
	s_cbranch_scc1 .Lgb12_have
	v_readlane_b32 s0, v254, 0
	v_readlane_b32 s1, v254, 1
	s_nop 4
	s_load_dwordx2 s[20:21], s[0:1], 0xe8
	s_load_dword s22, s[0:1], 0xf0
	v_mov_b32_e32 v5, 0
	v_mov_b32_e32 v6, 0x1000
	s_mov_b32 s19, 0
	s_waitcnt lgkmcnt(0)
	s_mul_i32 s20, s20, s21
	s_mul_i32 s20, s20, s22

.LBB0_2709:
	v_readlane_b32 s0, v254, 2
	v_readlane_b32 s1, v254, 3
	s_cmp_gt_i32 s1, 15
	s_cselect_b64 s[4:5], -1, 0
	s_and_b64 s[0:1], s[6:7], s[4:5]
	s_andn2_b64 vcc, exec, s[0:1]
	s_cbranch_vccnz .LBB0_2759
	s_waitcnt vmcnt(0) lgkmcnt(0)
	s_barrier
	v_readfirstlane_b32 s0, v0
	s_lshr_b32 s0, s0, 6
	s_cmp_lg_u32 s0, 0
	s_cbranch_scc1 .Lgb13_close
	s_mov_b64 s[10:11], exec
	s_mov_b64 exec, 1
	v_readlane_b32 s12, v254, 36
	v_readlane_b32 s13, v254, 37
	v_readlane_b32 s14, v254, 38
	v_readlane_b32 s15, v254, 39
	s_nop 1
	v_mov_b32_e32 v1, s14
	ds_read_b32 v2, v1
	ds_read_b32 v3, v1 offset:4
	ds_read_b32 v4, v1 offset:8
	s_waitcnt lgkmcnt(0)
	v_readfirstlane_b32 s16, v2
	v_readfirstlane_b32 s17, v3
	v_readfirstlane_b32 s18, v4
	s_cmp_lg_u32 s16, 0
	s_cbranch_scc1 .Lgb13_have
	v_readlane_b32 s0, v254, 0
	v_readlane_b32 s1, v254, 1
	s_nop 4
	s_load_dwordx2 s[20:21], s[0:1], 0xe8
	s_load_dword s22, s[0:1], 0xf0
	v_mov_b32_e32 v5, 0
	v_mov_b32_e32 v6, 0x1000
	s_mov_b32 s19, 0
	s_waitcnt lgkmcnt(0)
	s_mul_i32 s20, s20, s21
	s_mul_i32 s20, s20, s22

.LBB0_2799:
	v_readlane_b32 s0, v254, 2
	v_readlane_b32 s1, v254, 3
	s_cmp_gt_i32 s1, 16
	s_cselect_b64 s[4:5], -1, 0
	s_and_b64 s[0:1], s[8:9], s[4:5]
	s_andn2_b64 vcc, exec, s[0:1]
	s_cbranch_vccnz .LBB0_2849
	s_waitcnt vmcnt(0) lgkmcnt(0)
	s_barrier
	v_readfirstlane_b32 s0, v0
	s_lshr_b32 s0, s0, 6
	s_cmp_lg_u32 s0, 0
	s_cbranch_scc1 .Lgb14_close
	s_mov_b64 s[10:11], exec
	s_mov_b64 exec, 1
	v_readlane_b32 s12, v254, 36
	v_readlane_b32 s13, v254, 37
	v_readlane_b32 s14, v254, 38
	v_readlane_b32 s15, v254, 39
	s_nop 1
	v_mov_b32_e32 v1, s14
	ds_read_b32 v2, v1
	ds_read_b32 v3, v1 offset:4
	ds_read_b32 v4, v1 offset:8
	s_waitcnt lgkmcnt(0)
	v_readfirstlane_b32 s16, v2
	v_readfirstlane_b32 s17, v3
	v_readfirstlane_b32 s18, v4
	s_cmp_lg_u32 s16, 0
	s_cbranch_scc1 .Lgb14_have
	v_readlane_b32 s0, v254, 0
	v_readlane_b32 s1, v254, 1
	s_nop 4
	s_load_dwordx2 s[20:21], s[0:1], 0xe8
	s_load_dword s22, s[0:1], 0xf0
	v_mov_b32_e32 v5, 0
	v_mov_b32_e32 v6, 0x1000
	s_mov_b32 s19, 0
	s_waitcnt lgkmcnt(0)
	s_mul_i32 s20, s20, s21
	s_mul_i32 s20, s20, s22

.LBB0_3001:
	v_readlane_b32 s0, v254, 2
	v_readlane_b32 s1, v254, 3
	s_cmp_gt_i32 s1, 17
	s_cselect_b64 s[4:5], -1, 0
	s_and_b64 s[0:1], s[10:11], s[4:5]
	s_andn2_b64 vcc, exec, s[0:1]
	s_cbranch_vccnz .LBB0_3051
	s_waitcnt vmcnt(0) lgkmcnt(0)
	s_barrier
	v_readfirstlane_b32 s0, v0
	s_lshr_b32 s0, s0, 6
	s_cmp_lg_u32 s0, 0
	s_cbranch_scc1 .Lgb15_close
	s_mov_b64 s[10:11], exec
	s_mov_b64 exec, 1
	v_readlane_b32 s12, v254, 36
	v_readlane_b32 s13, v254, 37
	v_readlane_b32 s14, v254, 38
	v_readlane_b32 s15, v254, 39
	s_nop 1
	v_mov_b32_e32 v1, s14
	ds_read_b32 v2, v1
	ds_read_b32 v3, v1 offset:4
	ds_read_b32 v4, v1 offset:8
	s_waitcnt lgkmcnt(0)
	v_readfirstlane_b32 s16, v2
	v_readfirstlane_b32 s17, v3
	v_readfirstlane_b32 s18, v4
	s_cmp_lg_u32 s16, 0
	s_cbranch_scc1 .Lgb15_have
	v_readlane_b32 s0, v254, 0
	v_readlane_b32 s1, v254, 1
	s_nop 4
	s_load_dwordx2 s[20:21], s[0:1], 0xe8
	s_load_dword s22, s[0:1], 0xf0
	v_mov_b32_e32 v5, 0
	v_mov_b32_e32 v6, 0x1000
	s_mov_b32 s19, 0
	s_waitcnt lgkmcnt(0)
	s_mul_i32 s20, s20, s21
	s_mul_i32 s20, s20, s22
